# row-op phases: exact counted vmcnt(16) per row (loads of later rows and stores of earlier rows stay in flight)
# speedup vs baseline: 1.0014x; 1.0014x over previous
.Lgro2_r0_go:
	v_lshlrev_b32_e32 v48, 16, v168
	v_and_b32_e32 v49, 0xffff0000, v168
	v_lshlrev_b32_e32 v50, 16, v169
	v_and_b32_e32 v51, 0xffff0000, v169
	v_lshlrev_b32_e32 v52, 16, v170
	v_and_b32_e32 v53, 0xffff0000, v170
	v_lshlrev_b32_e32 v54, 16, v171
	v_and_b32_e32 v55, 0xffff0000, v171
	v_lshlrev_b32_e32 v56, 16, v172
	v_and_b32_e32 v57, 0xffff0000, v172
	v_lshlrev_b32_e32 v58, 16, v173
	v_and_b32_e32 v59, 0xffff0000, v173
	v_lshlrev_b32_e32 v60, 16, v174
	v_and_b32_e32 v61, 0xffff0000, v174
	v_lshlrev_b32_e32 v62, 16, v175
	v_and_b32_e32 v63, 0xffff0000, v175
	v_lshlrev_b32_e32 v64, 16, v176
	v_and_b32_e32 v65, 0xffff0000, v176
	v_lshlrev_b32_e32 v66, 16, v177
	v_and_b32_e32 v67, 0xffff0000, v177
	v_lshlrev_b32_e32 v68, 16, v178
	v_and_b32_e32 v69, 0xffff0000, v178
	v_lshlrev_b32_e32 v70, 16, v179
	v_and_b32_e32 v71, 0xffff0000, v179
	v_lshlrev_b32_e32 v72, 16, v180
	v_and_b32_e32 v73, 0xffff0000, v180
	v_lshlrev_b32_e32 v74, 16, v181
	v_and_b32_e32 v75, 0xffff0000, v181
	v_lshlrev_b32_e32 v76, 16, v182
	v_and_b32_e32 v77, 0xffff0000, v182
	v_lshlrev_b32_e32 v78, 16, v183
	v_and_b32_e32 v79, 0xffff0000, v183
	v_mul_f32_e32 v88, v64, v64
	v_mul_f32_e32 v89, v65, v65
	v_mul_f32_e32 v90, v66, v66
	v_mul_f32_e32 v91, v67, v67
	v_fmac_f32_e32 v88, v68, v68
	v_fmac_f32_e32 v89, v69, v69
	v_fmac_f32_e32 v90, v70, v70
	v_fmac_f32_e32 v91, v71, v71
	v_fmac_f32_e32 v88, v72, v72
	v_fmac_f32_e32 v89, v73, v73
	v_fmac_f32_e32 v90, v74, v74
	v_fmac_f32_e32 v91, v75, v75
	v_fmac_f32_e32 v88, v76, v76
	v_fmac_f32_e32 v89, v77, v77
	v_fmac_f32_e32 v90, v78, v78
	v_fmac_f32_e32 v91, v79, v79
	v_add_f32_e32 v88, v88, v89
	v_add_f32_e32 v90, v90, v91
	v_add_f32_e32 v84, v88, v90
	s_nop 1
	v_add_f32_dpp v84, v84, v84 quad_perm:[1,0,3,2] row_mask:0xf bank_mask:0xf bound_ctrl:1
	s_nop 1
	v_add_f32_dpp v84, v84, v84 quad_perm:[2,3,0,1] row_mask:0xf bank_mask:0xf bound_ctrl:1
	s_nop 1
	v_add_f32_dpp v84, v84, v84 row_half_mirror row_mask:0xf bank_mask:0xf bound_ctrl:1
	s_nop 1
	v_add_f32_dpp v84, v84, v84 row_mirror row_mask:0xf bank_mask:0xf bound_ctrl:1
	s_nop 0
	v_readlane_b32 s44, v84, 0
	v_readlane_b32 s46, v84, 16
	v_readlane_b32 s48, v84, 32
	v_readlane_b32 s50, v84, 48
	s_nop 0
	v_mov_b32_e32 v85, s44
	v_mov_b32_e32 v86, s48
	v_add_f32_e32 v85, s46, v85
	v_add_f32_e32 v86, s50, v86
	v_add_f32_e32 v84, v85, v86
	v_fmamk_f32 v84, v84, 0x3a800000, v130
	v_rsq_f32_e32 v84, v84
	s_nop 0
	v_mul_f32_e32 v92, v84, v64
	v_fmac_f32_e32 v48, v0, v92
	v_mul_f32_e32 v93, v84, v65
	v_fmac_f32_e32 v49, v1, v93
	v_mul_f32_e32 v94, v84, v66
	v_fmac_f32_e32 v50, v2, v94
	v_mul_f32_e32 v95, v84, v67
	v_fmac_f32_e32 v51, v3, v95
	v_mul_f32_e32 v92, v84, v68
	v_fmac_f32_e32 v52, v4, v92
	v_mul_f32_e32 v93, v84, v69
	v_fmac_f32_e32 v53, v5, v93
	v_mul_f32_e32 v94, v84, v70
	v_fmac_f32_e32 v54, v6, v94
	v_mul_f32_e32 v95, v84, v71
	v_fmac_f32_e32 v55, v7, v95
	v_mul_f32_e32 v92, v84, v72
	v_fmac_f32_e32 v56, v8, v92
	v_mul_f32_e32 v93, v84, v73
	v_fmac_f32_e32 v57, v9, v93
	v_mul_f32_e32 v94, v84, v74
	v_fmac_f32_e32 v58, v10, v94
	v_mul_f32_e32 v95, v84, v75
	v_fmac_f32_e32 v59, v11, v95
	v_mul_f32_e32 v92, v84, v76
	v_fmac_f32_e32 v60, v12, v92
	v_mul_f32_e32 v93, v84, v77
	v_fmac_f32_e32 v61, v13, v93
	v_mul_f32_e32 v94, v84, v78
	v_fmac_f32_e32 v62, v14, v94
	v_mul_f32_e32 v95, v84, v79
	v_fmac_f32_e32 v63, v15, v95
	s_lshl_b32 s21, s20, 11
	s_add_u32 s22, s86, s21
	s_addc_u32 s23, s87, 0
	v_cvt_pk_bf16_f32 v100, v48, v49
	v_cvt_pk_bf16_f32 v101, v50, v51
	v_cvt_pk_bf16_f32 v102, v52, v53
	v_cvt_pk_bf16_f32 v103, v54, v55
	v_cvt_pk_bf16_f32 v104, v56, v57
	v_cvt_pk_bf16_f32 v105, v58, v59
	v_cvt_pk_bf16_f32 v106, v60, v61
	v_cvt_pk_bf16_f32 v107, v62, v63
	global_store_dwordx4 v82, v[100:103], s[22:23]
	global_store_dwordx4 v82, v[104:107], s[22:23] offset:1024
	v_mul_f32_e32 v88, v48, v48
	v_mul_f32_e32 v89, v49, v49
	v_mul_f32_e32 v90, v50, v50
	v_mul_f32_e32 v91, v51, v51
	v_fmac_f32_e32 v88, v52, v52
	v_fmac_f32_e32 v89, v53, v53
	v_fmac_f32_e32 v90, v54, v54
	v_fmac_f32_e32 v91, v55, v55
	v_fmac_f32_e32 v88, v56, v56
	v_fmac_f32_e32 v89, v57, v57
	v_fmac_f32_e32 v90, v58, v58
	v_fmac_f32_e32 v91, v59, v59
	v_fmac_f32_e32 v88, v60, v60
	v_fmac_f32_e32 v89, v61, v61
	v_fmac_f32_e32 v90, v62, v62
	v_fmac_f32_e32 v91, v63, v63
	v_add_f32_e32 v88, v88, v89
	v_add_f32_e32 v90, v90, v91
	v_add_f32_e32 v84, v88, v90
	s_nop 1
	v_add_f32_dpp v84, v84, v84 quad_perm:[1,0,3,2] row_mask:0xf bank_mask:0xf bound_ctrl:1
	s_nop 1
	v_add_f32_dpp v84, v84, v84 quad_perm:[2,3,0,1] row_mask:0xf bank_mask:0xf bound_ctrl:1
	s_nop 1
	v_add_f32_dpp v84, v84, v84 row_half_mirror row_mask:0xf bank_mask:0xf bound_ctrl:1
	s_nop 1
	v_add_f32_dpp v84, v84, v84 row_mirror row_mask:0xf bank_mask:0xf bound_ctrl:1
	s_nop 0
	v_readlane_b32 s44, v84, 0
	v_readlane_b32 s46, v84, 16
	v_readlane_b32 s48, v84, 32
	v_readlane_b32 s50, v84, 48
	s_nop 0
	v_mov_b32_e32 v85, s44
	v_mov_b32_e32 v86, s48
	v_add_f32_e32 v85, s46, v85
	v_add_f32_e32 v86, s50, v86
	v_add_f32_e32 v84, v85, v86
	v_fmamk_f32 v84, v84, 0x3a800000, v130
	v_rsq_f32_e32 v84, v84
	s_nop 0
	v_mul_f32_e32 v92, v48, v84
	v_fma_f32 v64, v92, v32, v16
	v_mul_f32_e32 v93, v49, v84
	v_fma_f32 v65, v93, v33, v17
	v_mul_f32_e32 v94, v50, v84
	v_fma_f32 v66, v94, v34, v18
	v_mul_f32_e32 v95, v51, v84
	v_fma_f32 v67, v95, v35, v19
	v_mul_f32_e32 v92, v52, v84
	v_fma_f32 v68, v92, v36, v20
	v_mul_f32_e32 v93, v53, v84
	v_fma_f32 v69, v93, v37, v21
	v_mul_f32_e32 v94, v54, v84
	v_fma_f32 v70, v94, v38, v22
	v_mul_f32_e32 v95, v55, v84
	v_fma_f32 v71, v95, v39, v23
	v_mul_f32_e32 v92, v56, v84
	v_fma_f32 v72, v92, v40, v24
	v_mul_f32_e32 v93, v57, v84
	v_fma_f32 v73, v93, v41, v25
	v_mul_f32_e32 v94, v58, v84
	v_fma_f32 v74, v94, v42, v26
	v_mul_f32_e32 v95, v59, v84
	v_fma_f32 v75, v95, v43, v27
	v_mul_f32_e32 v92, v60, v84
	v_fma_f32 v76, v92, v44, v28
	v_mul_f32_e32 v93, v61, v84
	v_fma_f32 v77, v93, v45, v29
	v_mul_f32_e32 v94, v62, v84
	v_fma_f32 v78, v94, v46, v30
	v_mul_f32_e32 v95, v63, v84
	v_fma_f32 v79, v95, v47, v31
	s_add_u32 s22, s18, s21
	s_addc_u32 s23, s19, 0
	v_cvt_pk_bf16_f32 v108, v64, v65
	v_cvt_pk_bf16_f32 v109, v66, v67
	v_cvt_pk_bf16_f32 v110, v68, v69
	v_cvt_pk_bf16_f32 v111, v70, v71
	v_cvt_pk_bf16_f32 v112, v72, v73
	v_cvt_pk_bf16_f32 v113, v74, v75
	v_cvt_pk_bf16_f32 v114, v76, v77
	v_cvt_pk_bf16_f32 v115, v78, v79
	global_store_dwordx4 v82, v[108:111], s[22:23]
	global_store_dwordx4 v82, v[112:115], s[22:23] offset:1024
	s_add_u32 s20, s20, s14
	s_cmp_ge_u32 s20, 0x2800
	s_cbranch_scc1 .Lgro2_bend
	s_sub_u32 s4, s20, 0x2000
	s_lshr_b32 s4, s4, 10
	s_add_u32 s4, s4, 1
	s_cmp_lt_u32 s20, 0x2000
	s_cselect_b32 s4, 0, s4
	s_cmp_eq_u32 s4, s15
	s_cbranch_scc1 .Lgro2_r1_same
	s_mov_b32 s15, s4
	s_mul_i32 s4, s4, 0x9000
	s_add_u32 s32, s4, s6
	s_add_u32 s22, s16, s32
	s_addc_u32 s23, s17, 0
	global_load_dwordx4 v[0:3], v83, s[22:23]
	global_load_dwordx4 v[4:7], v83, s[22:23] offset:16
	global_load_dwordx4 v[8:11], v83, s[22:23] offset:2048
	global_load_dwordx4 v[12:15], v83, s[22:23] offset:2064
	s_add_u32 s32, s4, s7
	s_add_u32 s22, s16, s32
	s_addc_u32 s23, s17, 0
	global_load_dwordx4 v[16:19], v83, s[22:23]
	global_load_dwordx4 v[20:23], v83, s[22:23] offset:16
	global_load_dwordx4 v[24:27], v83, s[22:23] offset:2048
	global_load_dwordx4 v[28:31], v83, s[22:23] offset:2064
	s_add_u32 s22, s22, 0x1000
	s_addc_u32 s23, s23, 0
	global_load_dwordx4 v[32:35], v83, s[22:23]
	global_load_dwordx4 v[36:39], v83, s[22:23] offset:16
	global_load_dwordx4 v[40:43], v83, s[22:23] offset:2048
	global_load_dwordx4 v[44:47], v83, s[22:23] offset:2064
	s_waitcnt vmcnt(0)
	s_branch .Lgro2_r1_go
.Lgro2_r1_same:
	s_waitcnt vmcnt(16)
.Lgro2_r1_go:
	v_lshlrev_b32_e32 v48, 16, v184
	v_and_b32_e32 v49, 0xffff0000, v184
	v_lshlrev_b32_e32 v50, 16, v185
	v_and_b32_e32 v51, 0xffff0000, v185
	v_lshlrev_b32_e32 v52, 16, v186
	v_and_b32_e32 v53, 0xffff0000, v186
	v_lshlrev_b32_e32 v54, 16, v187
	v_and_b32_e32 v55, 0xffff0000, v187
	v_lshlrev_b32_e32 v56, 16, v188
	v_and_b32_e32 v57, 0xffff0000, v188
	v_lshlrev_b32_e32 v58, 16, v189
	v_and_b32_e32 v59, 0xffff0000, v189
	v_lshlrev_b32_e32 v60, 16, v190
	v_and_b32_e32 v61, 0xffff0000, v190
	v_lshlrev_b32_e32 v62, 16, v191
	v_and_b32_e32 v63, 0xffff0000, v191
	v_lshlrev_b32_e32 v64, 16, v192
	v_and_b32_e32 v65, 0xffff0000, v192
	v_lshlrev_b32_e32 v66, 16, v193
	v_and_b32_e32 v67, 0xffff0000, v193
	v_lshlrev_b32_e32 v68, 16, v194
	v_and_b32_e32 v69, 0xffff0000, v194
	v_lshlrev_b32_e32 v70, 16, v195
	v_and_b32_e32 v71, 0xffff0000, v195
	v_lshlrev_b32_e32 v72, 16, v196
	v_and_b32_e32 v73, 0xffff0000, v196
	v_lshlrev_b32_e32 v74, 16, v197
	v_and_b32_e32 v75, 0xffff0000, v197
	v_lshlrev_b32_e32 v76, 16, v198
	v_and_b32_e32 v77, 0xffff0000, v198
	v_lshlrev_b32_e32 v78, 16, v199
	v_and_b32_e32 v79, 0xffff0000, v199
	v_mul_f32_e32 v88, v64, v64
	v_mul_f32_e32 v89, v65, v65
	v_mul_f32_e32 v90, v66, v66
	v_mul_f32_e32 v91, v67, v67
	v_fmac_f32_e32 v88, v68, v68
	v_fmac_f32_e32 v89, v69, v69
	v_fmac_f32_e32 v90, v70, v70
	v_fmac_f32_e32 v91, v71, v71
	v_fmac_f32_e32 v88, v72, v72
	v_fmac_f32_e32 v89, v73, v73
	v_fmac_f32_e32 v90, v74, v74
	v_fmac_f32_e32 v91, v75, v75
	v_fmac_f32_e32 v88, v76, v76
	v_fmac_f32_e32 v89, v77, v77
	v_fmac_f32_e32 v90, v78, v78
	v_fmac_f32_e32 v91, v79, v79
	v_add_f32_e32 v88, v88, v89
	v_add_f32_e32 v90, v90, v91
	v_add_f32_e32 v84, v88, v90
	s_nop 1
	v_add_f32_dpp v84, v84, v84 quad_perm:[1,0,3,2] row_mask:0xf bank_mask:0xf bound_ctrl:1
	s_nop 1
	v_add_f32_dpp v84, v84, v84 quad_perm:[2,3,0,1] row_mask:0xf bank_mask:0xf bound_ctrl:1
	s_nop 1
	v_add_f32_dpp v84, v84, v84 row_half_mirror row_mask:0xf bank_mask:0xf bound_ctrl:1
	s_nop 1
	v_add_f32_dpp v84, v84, v84 row_mirror row_mask:0xf bank_mask:0xf bound_ctrl:1
	s_nop 0
	v_readlane_b32 s44, v84, 0
	v_readlane_b32 s46, v84, 16
	v_readlane_b32 s48, v84, 32
	v_readlane_b32 s50, v84, 48
	s_nop 0
	v_mov_b32_e32 v85, s44
	v_mov_b32_e32 v86, s48
	v_add_f32_e32 v85, s46, v85
	v_add_f32_e32 v86, s50, v86
	v_add_f32_e32 v84, v85, v86
	v_fmamk_f32 v84, v84, 0x3a800000, v130
	v_rsq_f32_e32 v84, v84
	s_nop 0
	v_mul_f32_e32 v92, v84, v64
	v_fmac_f32_e32 v48, v0, v92
	v_mul_f32_e32 v93, v84, v65
	v_fmac_f32_e32 v49, v1, v93
	v_mul_f32_e32 v94, v84, v66
	v_fmac_f32_e32 v50, v2, v94
	v_mul_f32_e32 v95, v84, v67
	v_fmac_f32_e32 v51, v3, v95
	v_mul_f32_e32 v92, v84, v68
	v_fmac_f32_e32 v52, v4, v92
	v_mul_f32_e32 v93, v84, v69
	v_fmac_f32_e32 v53, v5, v93
	v_mul_f32_e32 v94, v84, v70
	v_fmac_f32_e32 v54, v6, v94
	v_mul_f32_e32 v95, v84, v71
	v_fmac_f32_e32 v55, v7, v95
	v_mul_f32_e32 v92, v84, v72
	v_fmac_f32_e32 v56, v8, v92
	v_mul_f32_e32 v93, v84, v73
	v_fmac_f32_e32 v57, v9, v93
	v_mul_f32_e32 v94, v84, v74
	v_fmac_f32_e32 v58, v10, v94
	v_mul_f32_e32 v95, v84, v75
	v_fmac_f32_e32 v59, v11, v95
	v_mul_f32_e32 v92, v84, v76
	v_fmac_f32_e32 v60, v12, v92
	v_mul_f32_e32 v93, v84, v77
	v_fmac_f32_e32 v61, v13, v93
	v_mul_f32_e32 v94, v84, v78
	v_fmac_f32_e32 v62, v14, v94
	v_mul_f32_e32 v95, v84, v79
	v_fmac_f32_e32 v63, v15, v95
	s_lshl_b32 s21, s20, 11
	s_add_u32 s22, s86, s21
	s_addc_u32 s23, s87, 0
	v_cvt_pk_bf16_f32 v100, v48, v49
	v_cvt_pk_bf16_f32 v101, v50, v51
	v_cvt_pk_bf16_f32 v102, v52, v53
	v_cvt_pk_bf16_f32 v103, v54, v55
	v_cvt_pk_bf16_f32 v104, v56, v57
	v_cvt_pk_bf16_f32 v105, v58, v59
	v_cvt_pk_bf16_f32 v106, v60, v61
	v_cvt_pk_bf16_f32 v107, v62, v63
	global_store_dwordx4 v82, v[100:103], s[22:23]
	global_store_dwordx4 v82, v[104:107], s[22:23] offset:1024
	v_mul_f32_e32 v88, v48, v48
	v_mul_f32_e32 v89, v49, v49
	v_mul_f32_e32 v90, v50, v50
	v_mul_f32_e32 v91, v51, v51
	v_fmac_f32_e32 v88, v52, v52
	v_fmac_f32_e32 v89, v53, v53
	v_fmac_f32_e32 v90, v54, v54
	v_fmac_f32_e32 v91, v55, v55
	v_fmac_f32_e32 v88, v56, v56
	v_fmac_f32_e32 v89, v57, v57
	v_fmac_f32_e32 v90, v58, v58
	v_fmac_f32_e32 v91, v59, v59
	v_fmac_f32_e32 v88, v60, v60
	v_fmac_f32_e32 v89, v61, v61
	v_fmac_f32_e32 v90, v62, v62
	v_fmac_f32_e32 v91, v63, v63
	v_add_f32_e32 v88, v88, v89
	v_add_f32_e32 v90, v90, v91
	v_add_f32_e32 v84, v88, v90
	s_nop 1
	v_add_f32_dpp v84, v84, v84 quad_perm:[1,0,3,2] row_mask:0xf bank_mask:0xf bound_ctrl:1
	s_nop 1
	v_add_f32_dpp v84, v84, v84 quad_perm:[2,3,0,1] row_mask:0xf bank_mask:0xf bound_ctrl:1
	s_nop 1
	v_add_f32_dpp v84, v84, v84 row_half_mirror row_mask:0xf bank_mask:0xf bound_ctrl:1
	s_nop 1
	v_add_f32_dpp v84, v84, v84 row_mirror row_mask:0xf bank_mask:0xf bound_ctrl:1
	s_nop 0
	v_readlane_b32 s44, v84, 0
	v_readlane_b32 s46, v84, 16
	v_readlane_b32 s48, v84, 32
	v_readlane_b32 s50, v84, 48
	s_nop 0
	v_mov_b32_e32 v85, s44
	v_mov_b32_e32 v86, s48
	v_add_f32_e32 v85, s46, v85
	v_add_f32_e32 v86, s50, v86
	v_add_f32_e32 v84, v85, v86
	v_fmamk_f32 v84, v84, 0x3a800000, v130
	v_rsq_f32_e32 v84, v84
	s_nop 0
	v_mul_f32_e32 v92, v48, v84
	v_fma_f32 v64, v92, v32, v16
	v_mul_f32_e32 v93, v49, v84
	v_fma_f32 v65, v93, v33, v17
	v_mul_f32_e32 v94, v50, v84
	v_fma_f32 v66, v94, v34, v18
	v_mul_f32_e32 v95, v51, v84
	v_fma_f32 v67, v95, v35, v19
	v_mul_f32_e32 v92, v52, v84
	v_fma_f32 v68, v92, v36, v20
	v_mul_f32_e32 v93, v53, v84
	v_fma_f32 v69, v93, v37, v21
	v_mul_f32_e32 v94, v54, v84
	v_fma_f32 v70, v94, v38, v22
	v_mul_f32_e32 v95, v55, v84
	v_fma_f32 v71, v95, v39, v23
	v_mul_f32_e32 v92, v56, v84
	v_fma_f32 v72, v92, v40, v24
	v_mul_f32_e32 v93, v57, v84
	v_fma_f32 v73, v93, v41, v25
	v_mul_f32_e32 v94, v58, v84
	v_fma_f32 v74, v94, v42, v26
	v_mul_f32_e32 v95, v59, v84
	v_fma_f32 v75, v95, v43, v27
	v_mul_f32_e32 v92, v60, v84
	v_fma_f32 v76, v92, v44, v28
	v_mul_f32_e32 v93, v61, v84
	v_fma_f32 v77, v93, v45, v29
	v_mul_f32_e32 v94, v62, v84
	v_fma_f32 v78, v94, v46, v30
	v_mul_f32_e32 v95, v63, v84
	v_fma_f32 v79, v95, v47, v31
	s_add_u32 s22, s18, s21
	s_addc_u32 s23, s19, 0
	v_cvt_pk_bf16_f32 v108, v64, v65
	v_cvt_pk_bf16_f32 v109, v66, v67
	v_cvt_pk_bf16_f32 v110, v68, v69
	v_cvt_pk_bf16_f32 v111, v70, v71
	v_cvt_pk_bf16_f32 v112, v72, v73
	v_cvt_pk_bf16_f32 v113, v74, v75
	v_cvt_pk_bf16_f32 v114, v76, v77
	v_cvt_pk_bf16_f32 v115, v78, v79
	global_store_dwordx4 v82, v[108:111], s[22:23]
	global_store_dwordx4 v82, v[112:115], s[22:23] offset:1024
	s_add_u32 s20, s20, s14
	s_cmp_ge_u32 s20, 0x2800
	s_cbranch_scc1 .Lgro2_bend
	s_sub_u32 s4, s20, 0x2000
	s_lshr_b32 s4, s4, 10
	s_add_u32 s4, s4, 1
	s_cmp_lt_u32 s20, 0x2000
	s_cselect_b32 s4, 0, s4
	s_cmp_eq_u32 s4, s15
	s_cbranch_scc1 .Lgro2_r2_same
	s_mov_b32 s15, s4
	s_mul_i32 s4, s4, 0x9000
	s_add_u32 s32, s4, s6
	s_add_u32 s22, s16, s32
	s_addc_u32 s23, s17, 0
	global_load_dwordx4 v[0:3], v83, s[22:23]
	global_load_dwordx4 v[4:7], v83, s[22:23] offset:16
	global_load_dwordx4 v[8:11], v83, s[22:23] offset:2048
	global_load_dwordx4 v[12:15], v83, s[22:23] offset:2064
	s_add_u32 s32, s4, s7
	s_add_u32 s22, s16, s32
	s_addc_u32 s23, s17, 0
	global_load_dwordx4 v[16:19], v83, s[22:23]
	global_load_dwordx4 v[20:23], v83, s[22:23] offset:16
	global_load_dwordx4 v[24:27], v83, s[22:23] offset:2048
	global_load_dwordx4 v[28:31], v83, s[22:23] offset:2064
	s_add_u32 s22, s22, 0x1000
	s_addc_u32 s23, s23, 0
	global_load_dwordx4 v[32:35], v83, s[22:23]
	global_load_dwordx4 v[36:39], v83, s[22:23] offset:16
	global_load_dwordx4 v[40:43], v83, s[22:23] offset:2048
	global_load_dwordx4 v[44:47], v83, s[22:23] offset:2064
	s_waitcnt vmcnt(0)
	s_branch .Lgro2_r2_go
.Lgro2_r2_same:
	s_waitcnt vmcnt(16)
.Lgro2_r2_go:
	v_lshlrev_b32_e32 v48, 16, v200
	v_and_b32_e32 v49, 0xffff0000, v200
	v_lshlrev_b32_e32 v50, 16, v201
	v_and_b32_e32 v51, 0xffff0000, v201
	v_lshlrev_b32_e32 v52, 16, v202
	v_and_b32_e32 v53, 0xffff0000, v202
	v_lshlrev_b32_e32 v54, 16, v203
	v_and_b32_e32 v55, 0xffff0000, v203
	v_lshlrev_b32_e32 v56, 16, v204
	v_and_b32_e32 v57, 0xffff0000, v204
	v_lshlrev_b32_e32 v58, 16, v205
	v_and_b32_e32 v59, 0xffff0000, v205
	v_lshlrev_b32_e32 v60, 16, v206
	v_and_b32_e32 v61, 0xffff0000, v206
	v_lshlrev_b32_e32 v62, 16, v207
	v_and_b32_e32 v63, 0xffff0000, v207
	v_lshlrev_b32_e32 v64, 16, v208
	v_and_b32_e32 v65, 0xffff0000, v208
	v_lshlrev_b32_e32 v66, 16, v209
	v_and_b32_e32 v67, 0xffff0000, v209
	v_lshlrev_b32_e32 v68, 16, v210
	v_and_b32_e32 v69, 0xffff0000, v210
	v_lshlrev_b32_e32 v70, 16, v211
	v_and_b32_e32 v71, 0xffff0000, v211
	v_lshlrev_b32_e32 v72, 16, v212
	v_and_b32_e32 v73, 0xffff0000, v212
	v_lshlrev_b32_e32 v74, 16, v213
	v_and_b32_e32 v75, 0xffff0000, v213
	v_lshlrev_b32_e32 v76, 16, v214
	v_and_b32_e32 v77, 0xffff0000, v214
	v_lshlrev_b32_e32 v78, 16, v215
	v_and_b32_e32 v79, 0xffff0000, v215
	v_mul_f32_e32 v88, v64, v64
	v_mul_f32_e32 v89, v65, v65
	v_mul_f32_e32 v90, v66, v66
	v_mul_f32_e32 v91, v67, v67
	v_fmac_f32_e32 v88, v68, v68
	v_fmac_f32_e32 v89, v69, v69
	v_fmac_f32_e32 v90, v70, v70
	v_fmac_f32_e32 v91, v71, v71
	v_fmac_f32_e32 v88, v72, v72
	v_fmac_f32_e32 v89, v73, v73
	v_fmac_f32_e32 v90, v74, v74
	v_fmac_f32_e32 v91, v75, v75
	v_fmac_f32_e32 v88, v76, v76
	v_fmac_f32_e32 v89, v77, v77
	v_fmac_f32_e32 v90, v78, v78
	v_fmac_f32_e32 v91, v79, v79
	v_add_f32_e32 v88, v88, v89
	v_add_f32_e32 v90, v90, v91
	v_add_f32_e32 v84, v88, v90
	s_nop 1
	v_add_f32_dpp v84, v84, v84 quad_perm:[1,0,3,2] row_mask:0xf bank_mask:0xf bound_ctrl:1
	s_nop 1
	v_add_f32_dpp v84, v84, v84 quad_perm:[2,3,0,1] row_mask:0xf bank_mask:0xf bound_ctrl:1
	s_nop 1
	v_add_f32_dpp v84, v84, v84 row_half_mirror row_mask:0xf bank_mask:0xf bound_ctrl:1
	s_nop 1
	v_add_f32_dpp v84, v84, v84 row_mirror row_mask:0xf bank_mask:0xf bound_ctrl:1
	s_nop 0
	v_readlane_b32 s44, v84, 0
	v_readlane_b32 s46, v84, 16
	v_readlane_b32 s48, v84, 32
	v_readlane_b32 s50, v84, 48
	s_nop 0
	v_mov_b32_e32 v85, s44
	v_mov_b32_e32 v86, s48
	v_add_f32_e32 v85, s46, v85
	v_add_f32_e32 v86, s50, v86
	v_add_f32_e32 v84, v85, v86
	v_fmamk_f32 v84, v84, 0x3a800000, v130
	v_rsq_f32_e32 v84, v84
	s_nop 0
	v_mul_f32_e32 v92, v84, v64
	v_fmac_f32_e32 v48, v0, v92
	v_mul_f32_e32 v93, v84, v65
	v_fmac_f32_e32 v49, v1, v93
	v_mul_f32_e32 v94, v84, v66
	v_fmac_f32_e32 v50, v2, v94
	v_mul_f32_e32 v95, v84, v67
	v_fmac_f32_e32 v51, v3, v95
	v_mul_f32_e32 v92, v84, v68
	v_fmac_f32_e32 v52, v4, v92
	v_mul_f32_e32 v93, v84, v69
	v_fmac_f32_e32 v53, v5, v93
	v_mul_f32_e32 v94, v84, v70
	v_fmac_f32_e32 v54, v6, v94
	v_mul_f32_e32 v95, v84, v71
	v_fmac_f32_e32 v55, v7, v95
	v_mul_f32_e32 v92, v84, v72
	v_fmac_f32_e32 v56, v8, v92
	v_mul_f32_e32 v93, v84, v73
	v_fmac_f32_e32 v57, v9, v93
	v_mul_f32_e32 v94, v84, v74
	v_fmac_f32_e32 v58, v10, v94
	v_mul_f32_e32 v95, v84, v75
	v_fmac_f32_e32 v59, v11, v95
	v_mul_f32_e32 v92, v84, v76
	v_fmac_f32_e32 v60, v12, v92
	v_mul_f32_e32 v93, v84, v77
	v_fmac_f32_e32 v61, v13, v93
	v_mul_f32_e32 v94, v84, v78
	v_fmac_f32_e32 v62, v14, v94
	v_mul_f32_e32 v95, v84, v79
	v_fmac_f32_e32 v63, v15, v95
	s_lshl_b32 s21, s20, 11
	s_add_u32 s22, s86, s21
	s_addc_u32 s23, s87, 0
	v_cvt_pk_bf16_f32 v100, v48, v49
	v_cvt_pk_bf16_f32 v101, v50, v51
	v_cvt_pk_bf16_f32 v102, v52, v53
	v_cvt_pk_bf16_f32 v103, v54, v55
	v_cvt_pk_bf16_f32 v104, v56, v57
	v_cvt_pk_bf16_f32 v105, v58, v59
	v_cvt_pk_bf16_f32 v106, v60, v61
	v_cvt_pk_bf16_f32 v107, v62, v63
	global_store_dwordx4 v82, v[100:103], s[22:23]
	global_store_dwordx4 v82, v[104:107], s[22:23] offset:1024
	v_mul_f32_e32 v88, v48, v48
	v_mul_f32_e32 v89, v49, v49
	v_mul_f32_e32 v90, v50, v50
	v_mul_f32_e32 v91, v51, v51
	v_fmac_f32_e32 v88, v52, v52
	v_fmac_f32_e32 v89, v53, v53
	v_fmac_f32_e32 v90, v54, v54
	v_fmac_f32_e32 v91, v55, v55
	v_fmac_f32_e32 v88, v56, v56
	v_fmac_f32_e32 v89, v57, v57
	v_fmac_f32_e32 v90, v58, v58
	v_fmac_f32_e32 v91, v59, v59
	v_fmac_f32_e32 v88, v60, v60
	v_fmac_f32_e32 v89, v61, v61
	v_fmac_f32_e32 v90, v62, v62
	v_fmac_f32_e32 v91, v63, v63
	v_add_f32_e32 v88, v88, v89
	v_add_f32_e32 v90, v90, v91
	v_add_f32_e32 v84, v88, v90
	s_nop 1
	v_add_f32_dpp v84, v84, v84 quad_perm:[1,0,3,2] row_mask:0xf bank_mask:0xf bound_ctrl:1
	s_nop 1
	v_add_f32_dpp v84, v84, v84 quad_perm:[2,3,0,1] row_mask:0xf bank_mask:0xf bound_ctrl:1
	s_nop 1
	v_add_f32_dpp v84, v84, v84 row_half_mirror row_mask:0xf bank_mask:0xf bound_ctrl:1
	s_nop 1
	v_add_f32_dpp v84, v84, v84 row_mirror row_mask:0xf bank_mask:0xf bound_ctrl:1
	s_nop 0
	v_readlane_b32 s44, v84, 0
	v_readlane_b32 s46, v84, 16
	v_readlane_b32 s48, v84, 32
	v_readlane_b32 s50, v84, 48
	s_nop 0
	v_mov_b32_e32 v85, s44
	v_mov_b32_e32 v86, s48
	v_add_f32_e32 v85, s46, v85
	v_add_f32_e32 v86, s50, v86
	v_add_f32_e32 v84, v85, v86
	v_fmamk_f32 v84, v84, 0x3a800000, v130
	v_rsq_f32_e32 v84, v84
	s_nop 0
	v_mul_f32_e32 v92, v48, v84
	v_fma_f32 v64, v92, v32, v16
	v_mul_f32_e32 v93, v49, v84
	v_fma_f32 v65, v93, v33, v17
	v_mul_f32_e32 v94, v50, v84
	v_fma_f32 v66, v94, v34, v18
	v_mul_f32_e32 v95, v51, v84
	v_fma_f32 v67, v95, v35, v19
	v_mul_f32_e32 v92, v52, v84
	v_fma_f32 v68, v92, v36, v20
	v_mul_f32_e32 v93, v53, v84
	v_fma_f32 v69, v93, v37, v21
	v_mul_f32_e32 v94, v54, v84
	v_fma_f32 v70, v94, v38, v22
	v_mul_f32_e32 v95, v55, v84
	v_fma_f32 v71, v95, v39, v23
	v_mul_f32_e32 v92, v56, v84
	v_fma_f32 v72, v92, v40, v24
	v_mul_f32_e32 v93, v57, v84
	v_fma_f32 v73, v93, v41, v25
	v_mul_f32_e32 v94, v58, v84
	v_fma_f32 v74, v94, v42, v26
	v_mul_f32_e32 v95, v59, v84
	v_fma_f32 v75, v95, v43, v27
	v_mul_f32_e32 v92, v60, v84
	v_fma_f32 v76, v92, v44, v28
	v_mul_f32_e32 v93, v61, v84
	v_fma_f32 v77, v93, v45, v29
	v_mul_f32_e32 v94, v62, v84
	v_fma_f32 v78, v94, v46, v30
	v_mul_f32_e32 v95, v63, v84
	v_fma_f32 v79, v95, v47, v31
	s_add_u32 s22, s18, s21
	s_addc_u32 s23, s19, 0
	v_cvt_pk_bf16_f32 v108, v64, v65
	v_cvt_pk_bf16_f32 v109, v66, v67
	v_cvt_pk_bf16_f32 v110, v68, v69
	v_cvt_pk_bf16_f32 v111, v70, v71
	v_cvt_pk_bf16_f32 v112, v72, v73
	v_cvt_pk_bf16_f32 v113, v74, v75
	v_cvt_pk_bf16_f32 v114, v76, v77
	v_cvt_pk_bf16_f32 v115, v78, v79
	global_store_dwordx4 v82, v[108:111], s[22:23]
	global_store_dwordx4 v82, v[112:115], s[22:23] offset:1024
	s_add_u32 s20, s20, s14
	s_cmp_ge_u32 s20, 0x2800
	s_cbranch_scc1 .Lgro2_bend
	s_sub_u32 s4, s20, 0x2000
	s_lshr_b32 s4, s4, 10
	s_add_u32 s4, s4, 1
	s_cmp_lt_u32 s20, 0x2000
	s_cselect_b32 s4, 0, s4
	s_cmp_eq_u32 s4, s15
	s_cbranch_scc1 .Lgro2_r3_same
	s_mov_b32 s15, s4
	s_mul_i32 s4, s4, 0x9000
	s_add_u32 s32, s4, s6
	s_add_u32 s22, s16, s32
	s_addc_u32 s23, s17, 0
	global_load_dwordx4 v[0:3], v83, s[22:23]
	global_load_dwordx4 v[4:7], v83, s[22:23] offset:16
	global_load_dwordx4 v[8:11], v83, s[22:23] offset:2048
	global_load_dwordx4 v[12:15], v83, s[22:23] offset:2064
	s_add_u32 s32, s4, s7
	s_add_u32 s22, s16, s32
	s_addc_u32 s23, s17, 0
	global_load_dwordx4 v[16:19], v83, s[22:23]
	global_load_dwordx4 v[20:23], v83, s[22:23] offset:16
	global_load_dwordx4 v[24:27], v83, s[22:23] offset:2048
	global_load_dwordx4 v[28:31], v83, s[22:23] offset:2064
	s_add_u32 s22, s22, 0x1000
	s_addc_u32 s23, s23, 0
	global_load_dwordx4 v[32:35], v83, s[22:23]
	global_load_dwordx4 v[36:39], v83, s[22:23] offset:16
	global_load_dwordx4 v[40:43], v83, s[22:23] offset:2048
	global_load_dwordx4 v[44:47], v83, s[22:23] offset:2064
	s_waitcnt vmcnt(0)
	s_branch .Lgro2_r3_go
.Lgro2_r3_same:
	s_waitcnt vmcnt(16)
.Lgro2_r3_go:
	v_lshlrev_b32_e32 v48, 16, v216
	v_and_b32_e32 v49, 0xffff0000, v216
	v_lshlrev_b32_e32 v50, 16, v217
	v_and_b32_e32 v51, 0xffff0000, v217
	v_lshlrev_b32_e32 v52, 16, v218
	v_and_b32_e32 v53, 0xffff0000, v218
	v_lshlrev_b32_e32 v54, 16, v219
	v_and_b32_e32 v55, 0xffff0000, v219
	v_lshlrev_b32_e32 v56, 16, v220
	v_and_b32_e32 v57, 0xffff0000, v220
	v_lshlrev_b32_e32 v58, 16, v221
	v_and_b32_e32 v59, 0xffff0000, v221
	v_lshlrev_b32_e32 v60, 16, v222
	v_and_b32_e32 v61, 0xffff0000, v222
	v_lshlrev_b32_e32 v62, 16, v223
	v_and_b32_e32 v63, 0xffff0000, v223
	v_lshlrev_b32_e32 v64, 16, v224
	v_and_b32_e32 v65, 0xffff0000, v224
	v_lshlrev_b32_e32 v66, 16, v225
	v_and_b32_e32 v67, 0xffff0000, v225
	v_lshlrev_b32_e32 v68, 16, v226
	v_and_b32_e32 v69, 0xffff0000, v226
	v_lshlrev_b32_e32 v70, 16, v227
	v_and_b32_e32 v71, 0xffff0000, v227
	v_lshlrev_b32_e32 v72, 16, v228
	v_and_b32_e32 v73, 0xffff0000, v228
	v_lshlrev_b32_e32 v74, 16, v229
	v_and_b32_e32 v75, 0xffff0000, v229
	v_lshlrev_b32_e32 v76, 16, v230
	v_and_b32_e32 v77, 0xffff0000, v230
	v_lshlrev_b32_e32 v78, 16, v231
	v_and_b32_e32 v79, 0xffff0000, v231
	v_mul_f32_e32 v88, v64, v64
	v_mul_f32_e32 v89, v65, v65
	v_mul_f32_e32 v90, v66, v66
	v_mul_f32_e32 v91, v67, v67
	v_fmac_f32_e32 v88, v68, v68
	v_fmac_f32_e32 v89, v69, v69
	v_fmac_f32_e32 v90, v70, v70
	v_fmac_f32_e32 v91, v71, v71
	v_fmac_f32_e32 v88, v72, v72
	v_fmac_f32_e32 v89, v73, v73
	v_fmac_f32_e32 v90, v74, v74
	v_fmac_f32_e32 v91, v75, v75
	v_fmac_f32_e32 v88, v76, v76
	v_fmac_f32_e32 v89, v77, v77
	v_fmac_f32_e32 v90, v78, v78
	v_fmac_f32_e32 v91, v79, v79
	v_add_f32_e32 v88, v88, v89
	v_add_f32_e32 v90, v90, v91
	v_add_f32_e32 v84, v88, v90
	s_nop 1
	v_add_f32_dpp v84, v84, v84 quad_perm:[1,0,3,2] row_mask:0xf bank_mask:0xf bound_ctrl:1
	s_nop 1
	v_add_f32_dpp v84, v84, v84 quad_perm:[2,3,0,1] row_mask:0xf bank_mask:0xf bound_ctrl:1
	s_nop 1
	v_add_f32_dpp v84, v84, v84 row_half_mirror row_mask:0xf bank_mask:0xf bound_ctrl:1
	s_nop 1
	v_add_f32_dpp v84, v84, v84 row_mirror row_mask:0xf bank_mask:0xf bound_ctrl:1
	s_nop 0
	v_readlane_b32 s44, v84, 0
	v_readlane_b32 s46, v84, 16
	v_readlane_b32 s48, v84, 32
	v_readlane_b32 s50, v84, 48
	s_nop 0
	v_mov_b32_e32 v85, s44
	v_mov_b32_e32 v86, s48
	v_add_f32_e32 v85, s46, v85
	v_add_f32_e32 v86, s50, v86
	v_add_f32_e32 v84, v85, v86
	v_fmamk_f32 v84, v84, 0x3a800000, v130
	v_rsq_f32_e32 v84, v84
	s_nop 0
	v_mul_f32_e32 v92, v84, v64
	v_fmac_f32_e32 v48, v0, v92
	v_mul_f32_e32 v93, v84, v65
	v_fmac_f32_e32 v49, v1, v93
	v_mul_f32_e32 v94, v84, v66
	v_fmac_f32_e32 v50, v2, v94
	v_mul_f32_e32 v95, v84, v67
	v_fmac_f32_e32 v51, v3, v95
	v_mul_f32_e32 v92, v84, v68
	v_fmac_f32_e32 v52, v4, v92
	v_mul_f32_e32 v93, v84, v69
	v_fmac_f32_e32 v53, v5, v93
	v_mul_f32_e32 v94, v84, v70
	v_fmac_f32_e32 v54, v6, v94
	v_mul_f32_e32 v95, v84, v71
	v_fmac_f32_e32 v55, v7, v95
	v_mul_f32_e32 v92, v84, v72
	v_fmac_f32_e32 v56, v8, v92
	v_mul_f32_e32 v93, v84, v73
	v_fmac_f32_e32 v57, v9, v93
	v_mul_f32_e32 v94, v84, v74
	v_fmac_f32_e32 v58, v10, v94
	v_mul_f32_e32 v95, v84, v75
	v_fmac_f32_e32 v59, v11, v95
	v_mul_f32_e32 v92, v84, v76
	v_fmac_f32_e32 v60, v12, v92
	v_mul_f32_e32 v93, v84, v77
	v_fmac_f32_e32 v61, v13, v93
	v_mul_f32_e32 v94, v84, v78
	v_fmac_f32_e32 v62, v14, v94
	v_mul_f32_e32 v95, v84, v79
	v_fmac_f32_e32 v63, v15, v95
	s_lshl_b32 s21, s20, 11
	s_add_u32 s22, s86, s21
	s_addc_u32 s23, s87, 0
	v_cvt_pk_bf16_f32 v100, v48, v49
	v_cvt_pk_bf16_f32 v101, v50, v51
	v_cvt_pk_bf16_f32 v102, v52, v53
	v_cvt_pk_bf16_f32 v103, v54, v55
	v_cvt_pk_bf16_f32 v104, v56, v57
	v_cvt_pk_bf16_f32 v105, v58, v59
	v_cvt_pk_bf16_f32 v106, v60, v61
	v_cvt_pk_bf16_f32 v107, v62, v63
	global_store_dwordx4 v82, v[100:103], s[22:23]
	global_store_dwordx4 v82, v[104:107], s[22:23] offset:1024
	v_mul_f32_e32 v88, v48, v48
	v_mul_f32_e32 v89, v49, v49
	v_mul_f32_e32 v90, v50, v50
	v_mul_f32_e32 v91, v51, v51
	v_fmac_f32_e32 v88, v52, v52
	v_fmac_f32_e32 v89, v53, v53
	v_fmac_f32_e32 v90, v54, v54
	v_fmac_f32_e32 v91, v55, v55
	v_fmac_f32_e32 v88, v56, v56
	v_fmac_f32_e32 v89, v57, v57
	v_fmac_f32_e32 v90, v58, v58
	v_fmac_f32_e32 v91, v59, v59
	v_fmac_f32_e32 v88, v60, v60
	v_fmac_f32_e32 v89, v61, v61
	v_fmac_f32_e32 v90, v62, v62
	v_fmac_f32_e32 v91, v63, v63
	v_add_f32_e32 v88, v88, v89
	v_add_f32_e32 v90, v90, v91
	v_add_f32_e32 v84, v88, v90
	s_nop 1
	v_add_f32_dpp v84, v84, v84 quad_perm:[1,0,3,2] row_mask:0xf bank_mask:0xf bound_ctrl:1
	s_nop 1
	v_add_f32_dpp v84, v84, v84 quad_perm:[2,3,0,1] row_mask:0xf bank_mask:0xf bound_ctrl:1
	s_nop 1
	v_add_f32_dpp v84, v84, v84 row_half_mirror row_mask:0xf bank_mask:0xf bound_ctrl:1
	s_nop 1
	v_add_f32_dpp v84, v84, v84 row_mirror row_mask:0xf bank_mask:0xf bound_ctrl:1
	s_nop 0
	v_readlane_b32 s44, v84, 0
	v_readlane_b32 s46, v84, 16
	v_readlane_b32 s48, v84, 32
	v_readlane_b32 s50, v84, 48
	s_nop 0
	v_mov_b32_e32 v85, s44
	v_mov_b32_e32 v86, s48
	v_add_f32_e32 v85, s46, v85
	v_add_f32_e32 v86, s50, v86
	v_add_f32_e32 v84, v85, v86
	v_fmamk_f32 v84, v84, 0x3a800000, v130
	v_rsq_f32_e32 v84, v84
	s_nop 0
	v_mul_f32_e32 v92, v48, v84
	v_fma_f32 v64, v92, v32, v16
	v_mul_f32_e32 v93, v49, v84
	v_fma_f32 v65, v93, v33, v17
	v_mul_f32_e32 v94, v50, v84
	v_fma_f32 v66, v94, v34, v18
	v_mul_f32_e32 v95, v51, v84
	v_fma_f32 v67, v95, v35, v19
	v_mul_f32_e32 v92, v52, v84
	v_fma_f32 v68, v92, v36, v20
	v_mul_f32_e32 v93, v53, v84
	v_fma_f32 v69, v93, v37, v21
	v_mul_f32_e32 v94, v54, v84
	v_fma_f32 v70, v94, v38, v22
	v_mul_f32_e32 v95, v55, v84
	v_fma_f32 v71, v95, v39, v23
	v_mul_f32_e32 v92, v56, v84
	v_fma_f32 v72, v92, v40, v24
	v_mul_f32_e32 v93, v57, v84
	v_fma_f32 v73, v93, v41, v25
	v_mul_f32_e32 v94, v58, v84
	v_fma_f32 v74, v94, v42, v26
	v_mul_f32_e32 v95, v59, v84
	v_fma_f32 v75, v95, v43, v27
	v_mul_f32_e32 v92, v60, v84
	v_fma_f32 v76, v92, v44, v28
	v_mul_f32_e32 v93, v61, v84
	v_fma_f32 v77, v93, v45, v29
	v_mul_f32_e32 v94, v62, v84
	v_fma_f32 v78, v94, v46, v30
	v_mul_f32_e32 v95, v63, v84
	v_fma_f32 v79, v95, v47, v31
	s_add_u32 s22, s18, s21
	s_addc_u32 s23, s19, 0
	v_cvt_pk_bf16_f32 v108, v64, v65
	v_cvt_pk_bf16_f32 v109, v66, v67
	v_cvt_pk_bf16_f32 v110, v68, v69
	v_cvt_pk_bf16_f32 v111, v70, v71
	v_cvt_pk_bf16_f32 v112, v72, v73
	v_cvt_pk_bf16_f32 v113, v74, v75
	v_cvt_pk_bf16_f32 v114, v76, v77
	v_cvt_pk_bf16_f32 v115, v78, v79
	global_store_dwordx4 v82, v[108:111], s[22:23]
	global_store_dwordx4 v82, v[112:115], s[22:23] offset:1024
	s_add_u32 s20, s20, s14
	s_cmp_ge_u32 s20, 0x2800
	s_cbranch_scc1 .Lgro2_bend
	s_sub_u32 s4, s20, 0x2000
	s_lshr_b32 s4, s4, 10
	s_add_u32 s4, s4, 1
	s_cmp_lt_u32 s20, 0x2000
	s_cselect_b32 s4, 0, s4
	s_cmp_eq_u32 s4, s15
	s_cbranch_scc1 .Lgro2_r4_same
	s_mov_b32 s15, s4
	s_mul_i32 s4, s4, 0x9000
	s_add_u32 s32, s4, s6
	s_add_u32 s22, s16, s32
	s_addc_u32 s23, s17, 0
	global_load_dwordx4 v[0:3], v83, s[22:23]
	global_load_dwordx4 v[4:7], v83, s[22:23] offset:16
	global_load_dwordx4 v[8:11], v83, s[22:23] offset:2048
	global_load_dwordx4 v[12:15], v83, s[22:23] offset:2064
	s_add_u32 s32, s4, s7
	s_add_u32 s22, s16, s32
	s_addc_u32 s23, s17, 0
	global_load_dwordx4 v[16:19], v83, s[22:23]
	global_load_dwordx4 v[20:23], v83, s[22:23] offset:16
	global_load_dwordx4 v[24:27], v83, s[22:23] offset:2048
	global_load_dwordx4 v[28:31], v83, s[22:23] offset:2064
	s_add_u32 s22, s22, 0x1000
	s_addc_u32 s23, s23, 0
	global_load_dwordx4 v[32:35], v83, s[22:23]
	global_load_dwordx4 v[36:39], v83, s[22:23] offset:16
	global_load_dwordx4 v[40:43], v83, s[22:23] offset:2048
	global_load_dwordx4 v[44:47], v83, s[22:23] offset:2064
	s_waitcnt vmcnt(0)
	s_branch .Lgro2_r4_go
.Lgro2_r4_same:
	s_waitcnt vmcnt(16)
.Lgro2_r4_go:
	v_lshlrev_b32_e32 v48, 16, v232
	v_and_b32_e32 v49, 0xffff0000, v232
	v_lshlrev_b32_e32 v50, 16, v233
	v_and_b32_e32 v51, 0xffff0000, v233
	v_lshlrev_b32_e32 v52, 16, v234
	v_and_b32_e32 v53, 0xffff0000, v234
	v_lshlrev_b32_e32 v54, 16, v235
	v_and_b32_e32 v55, 0xffff0000, v235
	v_lshlrev_b32_e32 v56, 16, v236
	v_and_b32_e32 v57, 0xffff0000, v236
	v_lshlrev_b32_e32 v58, 16, v237
	v_and_b32_e32 v59, 0xffff0000, v237
	v_lshlrev_b32_e32 v60, 16, v238
	v_and_b32_e32 v61, 0xffff0000, v238
	v_lshlrev_b32_e32 v62, 16, v239
	v_and_b32_e32 v63, 0xffff0000, v239
	v_lshlrev_b32_e32 v64, 16, v240
	v_and_b32_e32 v65, 0xffff0000, v240
	v_lshlrev_b32_e32 v66, 16, v241
	v_and_b32_e32 v67, 0xffff0000, v241
	v_lshlrev_b32_e32 v68, 16, v242
	v_and_b32_e32 v69, 0xffff0000, v242
	v_lshlrev_b32_e32 v70, 16, v243
	v_and_b32_e32 v71, 0xffff0000, v243
	v_lshlrev_b32_e32 v72, 16, v244
	v_and_b32_e32 v73, 0xffff0000, v244
	v_lshlrev_b32_e32 v74, 16, v245
	v_and_b32_e32 v75, 0xffff0000, v245
	v_lshlrev_b32_e32 v76, 16, v246
	v_and_b32_e32 v77, 0xffff0000, v246
	v_lshlrev_b32_e32 v78, 16, v247
	v_and_b32_e32 v79, 0xffff0000, v247
	v_mul_f32_e32 v88, v64, v64
	v_mul_f32_e32 v89, v65, v65
	v_mul_f32_e32 v90, v66, v66
	v_mul_f32_e32 v91, v67, v67
	v_fmac_f32_e32 v88, v68, v68
	v_fmac_f32_e32 v89, v69, v69
	v_fmac_f32_e32 v90, v70, v70
	v_fmac_f32_e32 v91, v71, v71
	v_fmac_f32_e32 v88, v72, v72
	v_fmac_f32_e32 v89, v73, v73
	v_fmac_f32_e32 v90, v74, v74
	v_fmac_f32_e32 v91, v75, v75
	v_fmac_f32_e32 v88, v76, v76
	v_fmac_f32_e32 v89, v77, v77
	v_fmac_f32_e32 v90, v78, v78
	v_fmac_f32_e32 v91, v79, v79
	v_add_f32_e32 v88, v88, v89
	v_add_f32_e32 v90, v90, v91
	v_add_f32_e32 v84, v88, v90
	s_nop 1
	v_add_f32_dpp v84, v84, v84 quad_perm:[1,0,3,2] row_mask:0xf bank_mask:0xf bound_ctrl:1
	s_nop 1
	v_add_f32_dpp v84, v84, v84 quad_perm:[2,3,0,1] row_mask:0xf bank_mask:0xf bound_ctrl:1
	s_nop 1
	v_add_f32_dpp v84, v84, v84 row_half_mirror row_mask:0xf bank_mask:0xf bound_ctrl:1
	s_nop 1
	v_add_f32_dpp v84, v84, v84 row_mirror row_mask:0xf bank_mask:0xf bound_ctrl:1
	s_nop 0
	v_readlane_b32 s44, v84, 0
	v_readlane_b32 s46, v84, 16
	v_readlane_b32 s48, v84, 32
	v_readlane_b32 s50, v84, 48
	s_nop 0
	v_mov_b32_e32 v85, s44
	v_mov_b32_e32 v86, s48
	v_add_f32_e32 v85, s46, v85
	v_add_f32_e32 v86, s50, v86
	v_add_f32_e32 v84, v85, v86
	v_fmamk_f32 v84, v84, 0x3a800000, v130
	v_rsq_f32_e32 v84, v84
	s_nop 0
	v_mul_f32_e32 v92, v84, v64
	v_fmac_f32_e32 v48, v0, v92
	v_mul_f32_e32 v93, v84, v65
	v_fmac_f32_e32 v49, v1, v93
	v_mul_f32_e32 v94, v84, v66
	v_fmac_f32_e32 v50, v2, v94
	v_mul_f32_e32 v95, v84, v67
	v_fmac_f32_e32 v51, v3, v95
	v_mul_f32_e32 v92, v84, v68
	v_fmac_f32_e32 v52, v4, v92
	v_mul_f32_e32 v93, v84, v69
	v_fmac_f32_e32 v53, v5, v93
	v_mul_f32_e32 v94, v84, v70
	v_fmac_f32_e32 v54, v6, v94
	v_mul_f32_e32 v95, v84, v71
	v_fmac_f32_e32 v55, v7, v95
	v_mul_f32_e32 v92, v84, v72
	v_fmac_f32_e32 v56, v8, v92
	v_mul_f32_e32 v93, v84, v73
	v_fmac_f32_e32 v57, v9, v93
	v_mul_f32_e32 v94, v84, v74
	v_fmac_f32_e32 v58, v10, v94
	v_mul_f32_e32 v95, v84, v75
	v_fmac_f32_e32 v59, v11, v95
	v_mul_f32_e32 v92, v84, v76
	v_fmac_f32_e32 v60, v12, v92
	v_mul_f32_e32 v93, v84, v77
	v_fmac_f32_e32 v61, v13, v93
	v_mul_f32_e32 v94, v84, v78
	v_fmac_f32_e32 v62, v14, v94
	v_mul_f32_e32 v95, v84, v79
	v_fmac_f32_e32 v63, v15, v95
	s_lshl_b32 s21, s20, 11
	s_add_u32 s22, s86, s21
	s_addc_u32 s23, s87, 0
	v_cvt_pk_bf16_f32 v100, v48, v49
	v_cvt_pk_bf16_f32 v101, v50, v51
	v_cvt_pk_bf16_f32 v102, v52, v53
	v_cvt_pk_bf16_f32 v103, v54, v55
	v_cvt_pk_bf16_f32 v104, v56, v57
	v_cvt_pk_bf16_f32 v105, v58, v59
	v_cvt_pk_bf16_f32 v106, v60, v61
	v_cvt_pk_bf16_f32 v107, v62, v63
	global_store_dwordx4 v82, v[100:103], s[22:23]
	global_store_dwordx4 v82, v[104:107], s[22:23] offset:1024
	v_mul_f32_e32 v88, v48, v48
	v_mul_f32_e32 v89, v49, v49
	v_mul_f32_e32 v90, v50, v50
	v_mul_f32_e32 v91, v51, v51
	v_fmac_f32_e32 v88, v52, v52
	v_fmac_f32_e32 v89, v53, v53
	v_fmac_f32_e32 v90, v54, v54
	v_fmac_f32_e32 v91, v55, v55
	v_fmac_f32_e32 v88, v56, v56
	v_fmac_f32_e32 v89, v57, v57
	v_fmac_f32_e32 v90, v58, v58
	v_fmac_f32_e32 v91, v59, v59
	v_fmac_f32_e32 v88, v60, v60
	v_fmac_f32_e32 v89, v61, v61
	v_fmac_f32_e32 v90, v62, v62
	v_fmac_f32_e32 v91, v63, v63
	v_add_f32_e32 v88, v88, v89
	v_add_f32_e32 v90, v90, v91
	v_add_f32_e32 v84, v88, v90
	s_nop 1
	v_add_f32_dpp v84, v84, v84 quad_perm:[1,0,3,2] row_mask:0xf bank_mask:0xf bound_ctrl:1
	s_nop 1
	v_add_f32_dpp v84, v84, v84 quad_perm:[2,3,0,1] row_mask:0xf bank_mask:0xf bound_ctrl:1
	s_nop 1
	v_add_f32_dpp v84, v84, v84 row_half_mirror row_mask:0xf bank_mask:0xf bound_ctrl:1
	s_nop 1
	v_add_f32_dpp v84, v84, v84 row_mirror row_mask:0xf bank_mask:0xf bound_ctrl:1
	s_nop 0
	v_readlane_b32 s44, v84, 0
	v_readlane_b32 s46, v84, 16
	v_readlane_b32 s48, v84, 32
	v_readlane_b32 s50, v84, 48
	s_nop 0
	v_mov_b32_e32 v85, s44
	v_mov_b32_e32 v86, s48
	v_add_f32_e32 v85, s46, v85
	v_add_f32_e32 v86, s50, v86
	v_add_f32_e32 v84, v85, v86
	v_fmamk_f32 v84, v84, 0x3a800000, v130
	v_rsq_f32_e32 v84, v84
	s_nop 0
	v_mul_f32_e32 v92, v48, v84
	v_fma_f32 v64, v92, v32, v16
	v_mul_f32_e32 v93, v49, v84
	v_fma_f32 v65, v93, v33, v17
	v_mul_f32_e32 v94, v50, v84
	v_fma_f32 v66, v94, v34, v18
	v_mul_f32_e32 v95, v51, v84
	v_fma_f32 v67, v95, v35, v19
	v_mul_f32_e32 v92, v52, v84
	v_fma_f32 v68, v92, v36, v20
	v_mul_f32_e32 v93, v53, v84
	v_fma_f32 v69, v93, v37, v21
	v_mul_f32_e32 v94, v54, v84
	v_fma_f32 v70, v94, v38, v22
	v_mul_f32_e32 v95, v55, v84
	v_fma_f32 v71, v95, v39, v23
	v_mul_f32_e32 v92, v56, v84
	v_fma_f32 v72, v92, v40, v24
	v_mul_f32_e32 v93, v57, v84
	v_fma_f32 v73, v93, v41, v25
	v_mul_f32_e32 v94, v58, v84
	v_fma_f32 v74, v94, v42, v26
	v_mul_f32_e32 v95, v59, v84
	v_fma_f32 v75, v95, v43, v27
	v_mul_f32_e32 v92, v60, v84
	v_fma_f32 v76, v92, v44, v28
	v_mul_f32_e32 v93, v61, v84
	v_fma_f32 v77, v93, v45, v29
	v_mul_f32_e32 v94, v62, v84
	v_fma_f32 v78, v94, v46, v30
	v_mul_f32_e32 v95, v63, v84
	v_fma_f32 v79, v95, v47, v31
	s_add_u32 s22, s18, s21
	s_addc_u32 s23, s19, 0
	v_cvt_pk_bf16_f32 v108, v64, v65
	v_cvt_pk_bf16_f32 v109, v66, v67
	v_cvt_pk_bf16_f32 v110, v68, v69
	v_cvt_pk_bf16_f32 v111, v70, v71
	v_cvt_pk_bf16_f32 v112, v72, v73
	v_cvt_pk_bf16_f32 v113, v74, v75
	v_cvt_pk_bf16_f32 v114, v76, v77
	v_cvt_pk_bf16_f32 v115, v78, v79
	global_store_dwordx4 v82, v[108:111], s[22:23]
	global_store_dwordx4 v82, v[112:115], s[22:23] offset:1024

.Lgro8_r0_go:
	v_lshlrev_b32_e32 v48, 16, v168
	v_and_b32_e32 v49, 0xffff0000, v168
	v_lshlrev_b32_e32 v50, 16, v169
	v_and_b32_e32 v51, 0xffff0000, v169
	v_lshlrev_b32_e32 v52, 16, v170
	v_and_b32_e32 v53, 0xffff0000, v170
	v_lshlrev_b32_e32 v54, 16, v171
	v_and_b32_e32 v55, 0xffff0000, v171
	v_lshlrev_b32_e32 v56, 16, v172
	v_and_b32_e32 v57, 0xffff0000, v172
	v_lshlrev_b32_e32 v58, 16, v173
	v_and_b32_e32 v59, 0xffff0000, v173
	v_lshlrev_b32_e32 v60, 16, v174
	v_and_b32_e32 v61, 0xffff0000, v174
	v_lshlrev_b32_e32 v62, 16, v175
	v_and_b32_e32 v63, 0xffff0000, v175
	v_lshlrev_b32_e32 v64, 16, v176
	v_and_b32_e32 v65, 0xffff0000, v176
	v_lshlrev_b32_e32 v66, 16, v177
	v_and_b32_e32 v67, 0xffff0000, v177
	v_lshlrev_b32_e32 v68, 16, v178
	v_and_b32_e32 v69, 0xffff0000, v178
	v_lshlrev_b32_e32 v70, 16, v179
	v_and_b32_e32 v71, 0xffff0000, v179
	v_lshlrev_b32_e32 v72, 16, v180
	v_and_b32_e32 v73, 0xffff0000, v180
	v_lshlrev_b32_e32 v74, 16, v181
	v_and_b32_e32 v75, 0xffff0000, v181
	v_lshlrev_b32_e32 v76, 16, v182
	v_and_b32_e32 v77, 0xffff0000, v182
	v_lshlrev_b32_e32 v78, 16, v183
	v_and_b32_e32 v79, 0xffff0000, v183
	v_mul_f32_e32 v88, v64, v64
	v_mul_f32_e32 v89, v65, v65
	v_mul_f32_e32 v90, v66, v66
	v_mul_f32_e32 v91, v67, v67
	v_fmac_f32_e32 v88, v68, v68
	v_fmac_f32_e32 v89, v69, v69
	v_fmac_f32_e32 v90, v70, v70
	v_fmac_f32_e32 v91, v71, v71
	v_fmac_f32_e32 v88, v72, v72
	v_fmac_f32_e32 v89, v73, v73
	v_fmac_f32_e32 v90, v74, v74
	v_fmac_f32_e32 v91, v75, v75
	v_fmac_f32_e32 v88, v76, v76
	v_fmac_f32_e32 v89, v77, v77
	v_fmac_f32_e32 v90, v78, v78
	v_fmac_f32_e32 v91, v79, v79
	v_add_f32_e32 v88, v88, v89
	v_add_f32_e32 v90, v90, v91
	v_add_f32_e32 v84, v88, v90
	s_nop 1
	v_add_f32_dpp v84, v84, v84 quad_perm:[1,0,3,2] row_mask:0xf bank_mask:0xf bound_ctrl:1
	s_nop 1
	v_add_f32_dpp v84, v84, v84 quad_perm:[2,3,0,1] row_mask:0xf bank_mask:0xf bound_ctrl:1
	s_nop 1
	v_add_f32_dpp v84, v84, v84 row_half_mirror row_mask:0xf bank_mask:0xf bound_ctrl:1
	s_nop 1
	v_add_f32_dpp v84, v84, v84 row_mirror row_mask:0xf bank_mask:0xf bound_ctrl:1
	s_nop 0
	v_readlane_b32 s44, v84, 0
	v_readlane_b32 s46, v84, 16
	v_readlane_b32 s48, v84, 32
	v_readlane_b32 s50, v84, 48
	s_nop 0
	v_mov_b32_e32 v85, s44
	v_mov_b32_e32 v86, s48
	v_add_f32_e32 v85, s46, v85
	v_add_f32_e32 v86, s50, v86
	v_add_f32_e32 v84, v85, v86
	v_fmamk_f32 v84, v84, 0x3a800000, v130
	v_rsq_f32_e32 v84, v84
	s_nop 0
	v_mul_f32_e32 v92, v84, v64
	v_fmac_f32_e32 v48, v0, v92
	v_mul_f32_e32 v93, v84, v65
	v_fmac_f32_e32 v49, v1, v93
	v_mul_f32_e32 v94, v84, v66
	v_fmac_f32_e32 v50, v2, v94
	v_mul_f32_e32 v95, v84, v67
	v_fmac_f32_e32 v51, v3, v95
	v_mul_f32_e32 v92, v84, v68
	v_fmac_f32_e32 v52, v4, v92
	v_mul_f32_e32 v93, v84, v69
	v_fmac_f32_e32 v53, v5, v93
	v_mul_f32_e32 v94, v84, v70
	v_fmac_f32_e32 v54, v6, v94
	v_mul_f32_e32 v95, v84, v71
	v_fmac_f32_e32 v55, v7, v95
	v_mul_f32_e32 v92, v84, v72
	v_fmac_f32_e32 v56, v8, v92
	v_mul_f32_e32 v93, v84, v73
	v_fmac_f32_e32 v57, v9, v93
	v_mul_f32_e32 v94, v84, v74
	v_fmac_f32_e32 v58, v10, v94
	v_mul_f32_e32 v95, v84, v75
	v_fmac_f32_e32 v59, v11, v95
	v_mul_f32_e32 v92, v84, v76
	v_fmac_f32_e32 v60, v12, v92
	v_mul_f32_e32 v93, v84, v77
	v_fmac_f32_e32 v61, v13, v93
	v_mul_f32_e32 v94, v84, v78
	v_fmac_f32_e32 v62, v14, v94
	v_mul_f32_e32 v95, v84, v79
	v_fmac_f32_e32 v63, v15, v95
	s_lshl_b32 s21, s20, 11
	s_add_u32 s22, s86, s21
	s_addc_u32 s23, s87, 0
	v_cvt_pk_bf16_f32 v100, v48, v49
	v_cvt_pk_bf16_f32 v101, v50, v51
	v_cvt_pk_bf16_f32 v102, v52, v53
	v_cvt_pk_bf16_f32 v103, v54, v55
	v_cvt_pk_bf16_f32 v104, v56, v57
	v_cvt_pk_bf16_f32 v105, v58, v59
	v_cvt_pk_bf16_f32 v106, v60, v61
	v_cvt_pk_bf16_f32 v107, v62, v63
	global_store_dwordx4 v82, v[100:103], s[22:23]
	global_store_dwordx4 v82, v[104:107], s[22:23] offset:1024
	v_mul_f32_e32 v88, v48, v48
	v_mul_f32_e32 v89, v49, v49
	v_mul_f32_e32 v90, v50, v50
	v_mul_f32_e32 v91, v51, v51
	v_fmac_f32_e32 v88, v52, v52
	v_fmac_f32_e32 v89, v53, v53
	v_fmac_f32_e32 v90, v54, v54
	v_fmac_f32_e32 v91, v55, v55
	v_fmac_f32_e32 v88, v56, v56
	v_fmac_f32_e32 v89, v57, v57
	v_fmac_f32_e32 v90, v58, v58
	v_fmac_f32_e32 v91, v59, v59
	v_fmac_f32_e32 v88, v60, v60
	v_fmac_f32_e32 v89, v61, v61
	v_fmac_f32_e32 v90, v62, v62
	v_fmac_f32_e32 v91, v63, v63
	v_add_f32_e32 v88, v88, v89
	v_add_f32_e32 v90, v90, v91
	v_add_f32_e32 v84, v88, v90
	s_nop 1
	v_add_f32_dpp v84, v84, v84 quad_perm:[1,0,3,2] row_mask:0xf bank_mask:0xf bound_ctrl:1
	s_nop 1
	v_add_f32_dpp v84, v84, v84 quad_perm:[2,3,0,1] row_mask:0xf bank_mask:0xf bound_ctrl:1
	s_nop 1
	v_add_f32_dpp v84, v84, v84 row_half_mirror row_mask:0xf bank_mask:0xf bound_ctrl:1
	s_nop 1
	v_add_f32_dpp v84, v84, v84 row_mirror row_mask:0xf bank_mask:0xf bound_ctrl:1
	s_nop 0
	v_readlane_b32 s44, v84, 0
	v_readlane_b32 s46, v84, 16
	v_readlane_b32 s48, v84, 32
	v_readlane_b32 s50, v84, 48
	s_nop 0
	v_mov_b32_e32 v85, s44
	v_mov_b32_e32 v86, s48
	v_add_f32_e32 v85, s46, v85
	v_add_f32_e32 v86, s50, v86
	v_add_f32_e32 v84, v85, v86
	v_fmamk_f32 v84, v84, 0x3a800000, v130
	v_rsq_f32_e32 v84, v84
	s_nop 0
	v_mul_f32_e32 v92, v48, v84
	v_fma_f32 v64, v92, v32, v16
	v_mul_f32_e32 v93, v49, v84
	v_fma_f32 v65, v93, v33, v17
	v_mul_f32_e32 v94, v50, v84
	v_fma_f32 v66, v94, v34, v18
	v_mul_f32_e32 v95, v51, v84
	v_fma_f32 v67, v95, v35, v19
	v_mul_f32_e32 v92, v52, v84
	v_fma_f32 v68, v92, v36, v20
	v_mul_f32_e32 v93, v53, v84
	v_fma_f32 v69, v93, v37, v21
	v_mul_f32_e32 v94, v54, v84
	v_fma_f32 v70, v94, v38, v22
	v_mul_f32_e32 v95, v55, v84
	v_fma_f32 v71, v95, v39, v23
	v_mul_f32_e32 v92, v56, v84
	v_fma_f32 v72, v92, v40, v24
	v_mul_f32_e32 v93, v57, v84
	v_fma_f32 v73, v93, v41, v25
	v_mul_f32_e32 v94, v58, v84
	v_fma_f32 v74, v94, v42, v26
	v_mul_f32_e32 v95, v59, v84
	v_fma_f32 v75, v95, v43, v27
	v_mul_f32_e32 v92, v60, v84
	v_fma_f32 v76, v92, v44, v28
	v_mul_f32_e32 v93, v61, v84
	v_fma_f32 v77, v93, v45, v29
	v_mul_f32_e32 v94, v62, v84
	v_fma_f32 v78, v94, v46, v30
	v_mul_f32_e32 v95, v63, v84
	v_fma_f32 v79, v95, v47, v31
	s_add_u32 s22, s18, s21
	s_addc_u32 s23, s19, 0
	v_cvt_pk_bf16_f32 v108, v64, v65
	v_cvt_pk_bf16_f32 v109, v66, v67
	v_cvt_pk_bf16_f32 v110, v68, v69
	v_cvt_pk_bf16_f32 v111, v70, v71
	v_cvt_pk_bf16_f32 v112, v72, v73
	v_cvt_pk_bf16_f32 v113, v74, v75
	v_cvt_pk_bf16_f32 v114, v76, v77
	v_cvt_pk_bf16_f32 v115, v78, v79
	global_store_dwordx4 v82, v[108:111], s[22:23]
	global_store_dwordx4 v82, v[112:115], s[22:23] offset:1024
	s_add_u32 s20, s20, s14
	s_cmp_ge_u32 s20, 0x2800
	s_cbranch_scc1 .Lgro8_bend
	s_sub_u32 s4, s20, 0x2000
	s_lshr_b32 s4, s4, 10
	s_add_u32 s4, s4, 1
	s_cmp_lt_u32 s20, 0x2000
	s_cselect_b32 s4, 0, s4
	s_cmp_eq_u32 s4, s15
	s_cbranch_scc1 .Lgro8_r1_same
	s_mov_b32 s15, s4
	s_mul_i32 s4, s4, 0x9000
	s_add_u32 s32, s4, s6
	s_add_u32 s22, s16, s32
	s_addc_u32 s23, s17, 0
	global_load_dwordx4 v[0:3], v83, s[22:23]
	global_load_dwordx4 v[4:7], v83, s[22:23] offset:16
	global_load_dwordx4 v[8:11], v83, s[22:23] offset:2048
	global_load_dwordx4 v[12:15], v83, s[22:23] offset:2064
	s_add_u32 s32, s4, s7
	s_add_u32 s22, s16, s32
	s_addc_u32 s23, s17, 0
	global_load_dwordx4 v[16:19], v83, s[22:23]
	global_load_dwordx4 v[20:23], v83, s[22:23] offset:16
	global_load_dwordx4 v[24:27], v83, s[22:23] offset:2048
	global_load_dwordx4 v[28:31], v83, s[22:23] offset:2064
	s_add_u32 s22, s22, 0x1000
	s_addc_u32 s23, s23, 0
	global_load_dwordx4 v[32:35], v83, s[22:23]
	global_load_dwordx4 v[36:39], v83, s[22:23] offset:16
	global_load_dwordx4 v[40:43], v83, s[22:23] offset:2048
	global_load_dwordx4 v[44:47], v83, s[22:23] offset:2064
	s_waitcnt vmcnt(0)
	s_branch .Lgro8_r1_go
.Lgro8_r1_same:
	s_waitcnt vmcnt(16)
.Lgro8_r1_go:
	v_lshlrev_b32_e32 v48, 16, v184
	v_and_b32_e32 v49, 0xffff0000, v184
	v_lshlrev_b32_e32 v50, 16, v185
	v_and_b32_e32 v51, 0xffff0000, v185
	v_lshlrev_b32_e32 v52, 16, v186
	v_and_b32_e32 v53, 0xffff0000, v186
	v_lshlrev_b32_e32 v54, 16, v187
	v_and_b32_e32 v55, 0xffff0000, v187
	v_lshlrev_b32_e32 v56, 16, v188
	v_and_b32_e32 v57, 0xffff0000, v188
	v_lshlrev_b32_e32 v58, 16, v189
	v_and_b32_e32 v59, 0xffff0000, v189
	v_lshlrev_b32_e32 v60, 16, v190
	v_and_b32_e32 v61, 0xffff0000, v190
	v_lshlrev_b32_e32 v62, 16, v191
	v_and_b32_e32 v63, 0xffff0000, v191
	v_lshlrev_b32_e32 v64, 16, v192
	v_and_b32_e32 v65, 0xffff0000, v192
	v_lshlrev_b32_e32 v66, 16, v193
	v_and_b32_e32 v67, 0xffff0000, v193
	v_lshlrev_b32_e32 v68, 16, v194
	v_and_b32_e32 v69, 0xffff0000, v194
	v_lshlrev_b32_e32 v70, 16, v195
	v_and_b32_e32 v71, 0xffff0000, v195
	v_lshlrev_b32_e32 v72, 16, v196
	v_and_b32_e32 v73, 0xffff0000, v196
	v_lshlrev_b32_e32 v74, 16, v197
	v_and_b32_e32 v75, 0xffff0000, v197
	v_lshlrev_b32_e32 v76, 16, v198
	v_and_b32_e32 v77, 0xffff0000, v198
	v_lshlrev_b32_e32 v78, 16, v199
	v_and_b32_e32 v79, 0xffff0000, v199
	v_mul_f32_e32 v88, v64, v64
	v_mul_f32_e32 v89, v65, v65
	v_mul_f32_e32 v90, v66, v66
	v_mul_f32_e32 v91, v67, v67
	v_fmac_f32_e32 v88, v68, v68
	v_fmac_f32_e32 v89, v69, v69
	v_fmac_f32_e32 v90, v70, v70
	v_fmac_f32_e32 v91, v71, v71
	v_fmac_f32_e32 v88, v72, v72
	v_fmac_f32_e32 v89, v73, v73
	v_fmac_f32_e32 v90, v74, v74
	v_fmac_f32_e32 v91, v75, v75
	v_fmac_f32_e32 v88, v76, v76
	v_fmac_f32_e32 v89, v77, v77
	v_fmac_f32_e32 v90, v78, v78
	v_fmac_f32_e32 v91, v79, v79
	v_add_f32_e32 v88, v88, v89
	v_add_f32_e32 v90, v90, v91
	v_add_f32_e32 v84, v88, v90
	s_nop 1
	v_add_f32_dpp v84, v84, v84 quad_perm:[1,0,3,2] row_mask:0xf bank_mask:0xf bound_ctrl:1
	s_nop 1
	v_add_f32_dpp v84, v84, v84 quad_perm:[2,3,0,1] row_mask:0xf bank_mask:0xf bound_ctrl:1
	s_nop 1
	v_add_f32_dpp v84, v84, v84 row_half_mirror row_mask:0xf bank_mask:0xf bound_ctrl:1
	s_nop 1
	v_add_f32_dpp v84, v84, v84 row_mirror row_mask:0xf bank_mask:0xf bound_ctrl:1
	s_nop 0
	v_readlane_b32 s44, v84, 0
	v_readlane_b32 s46, v84, 16
	v_readlane_b32 s48, v84, 32
	v_readlane_b32 s50, v84, 48
	s_nop 0
	v_mov_b32_e32 v85, s44
	v_mov_b32_e32 v86, s48
	v_add_f32_e32 v85, s46, v85
	v_add_f32_e32 v86, s50, v86
	v_add_f32_e32 v84, v85, v86
	v_fmamk_f32 v84, v84, 0x3a800000, v130
	v_rsq_f32_e32 v84, v84
	s_nop 0
	v_mul_f32_e32 v92, v84, v64
	v_fmac_f32_e32 v48, v0, v92
	v_mul_f32_e32 v93, v84, v65
	v_fmac_f32_e32 v49, v1, v93
	v_mul_f32_e32 v94, v84, v66
	v_fmac_f32_e32 v50, v2, v94
	v_mul_f32_e32 v95, v84, v67
	v_fmac_f32_e32 v51, v3, v95
	v_mul_f32_e32 v92, v84, v68
	v_fmac_f32_e32 v52, v4, v92
	v_mul_f32_e32 v93, v84, v69
	v_fmac_f32_e32 v53, v5, v93
	v_mul_f32_e32 v94, v84, v70
	v_fmac_f32_e32 v54, v6, v94
	v_mul_f32_e32 v95, v84, v71
	v_fmac_f32_e32 v55, v7, v95
	v_mul_f32_e32 v92, v84, v72
	v_fmac_f32_e32 v56, v8, v92
	v_mul_f32_e32 v93, v84, v73
	v_fmac_f32_e32 v57, v9, v93
	v_mul_f32_e32 v94, v84, v74
	v_fmac_f32_e32 v58, v10, v94
	v_mul_f32_e32 v95, v84, v75
	v_fmac_f32_e32 v59, v11, v95
	v_mul_f32_e32 v92, v84, v76
	v_fmac_f32_e32 v60, v12, v92
	v_mul_f32_e32 v93, v84, v77
	v_fmac_f32_e32 v61, v13, v93
	v_mul_f32_e32 v94, v84, v78
	v_fmac_f32_e32 v62, v14, v94
	v_mul_f32_e32 v95, v84, v79
	v_fmac_f32_e32 v63, v15, v95
	s_lshl_b32 s21, s20, 11
	s_add_u32 s22, s86, s21
	s_addc_u32 s23, s87, 0
	v_cvt_pk_bf16_f32 v100, v48, v49
	v_cvt_pk_bf16_f32 v101, v50, v51
	v_cvt_pk_bf16_f32 v102, v52, v53
	v_cvt_pk_bf16_f32 v103, v54, v55
	v_cvt_pk_bf16_f32 v104, v56, v57
	v_cvt_pk_bf16_f32 v105, v58, v59
	v_cvt_pk_bf16_f32 v106, v60, v61
	v_cvt_pk_bf16_f32 v107, v62, v63
	global_store_dwordx4 v82, v[100:103], s[22:23]
	global_store_dwordx4 v82, v[104:107], s[22:23] offset:1024
	v_mul_f32_e32 v88, v48, v48
	v_mul_f32_e32 v89, v49, v49
	v_mul_f32_e32 v90, v50, v50
	v_mul_f32_e32 v91, v51, v51
	v_fmac_f32_e32 v88, v52, v52
	v_fmac_f32_e32 v89, v53, v53
	v_fmac_f32_e32 v90, v54, v54
	v_fmac_f32_e32 v91, v55, v55
	v_fmac_f32_e32 v88, v56, v56
	v_fmac_f32_e32 v89, v57, v57
	v_fmac_f32_e32 v90, v58, v58
	v_fmac_f32_e32 v91, v59, v59
	v_fmac_f32_e32 v88, v60, v60
	v_fmac_f32_e32 v89, v61, v61
	v_fmac_f32_e32 v90, v62, v62
	v_fmac_f32_e32 v91, v63, v63
	v_add_f32_e32 v88, v88, v89
	v_add_f32_e32 v90, v90, v91
	v_add_f32_e32 v84, v88, v90
	s_nop 1
	v_add_f32_dpp v84, v84, v84 quad_perm:[1,0,3,2] row_mask:0xf bank_mask:0xf bound_ctrl:1
	s_nop 1
	v_add_f32_dpp v84, v84, v84 quad_perm:[2,3,0,1] row_mask:0xf bank_mask:0xf bound_ctrl:1
	s_nop 1
	v_add_f32_dpp v84, v84, v84 row_half_mirror row_mask:0xf bank_mask:0xf bound_ctrl:1
	s_nop 1
	v_add_f32_dpp v84, v84, v84 row_mirror row_mask:0xf bank_mask:0xf bound_ctrl:1
	s_nop 0
	v_readlane_b32 s44, v84, 0
	v_readlane_b32 s46, v84, 16
	v_readlane_b32 s48, v84, 32
	v_readlane_b32 s50, v84, 48
	s_nop 0
	v_mov_b32_e32 v85, s44
	v_mov_b32_e32 v86, s48
	v_add_f32_e32 v85, s46, v85
	v_add_f32_e32 v86, s50, v86
	v_add_f32_e32 v84, v85, v86
	v_fmamk_f32 v84, v84, 0x3a800000, v130
	v_rsq_f32_e32 v84, v84
	s_nop 0
	v_mul_f32_e32 v92, v48, v84
	v_fma_f32 v64, v92, v32, v16
	v_mul_f32_e32 v93, v49, v84
	v_fma_f32 v65, v93, v33, v17
	v_mul_f32_e32 v94, v50, v84
	v_fma_f32 v66, v94, v34, v18
	v_mul_f32_e32 v95, v51, v84
	v_fma_f32 v67, v95, v35, v19
	v_mul_f32_e32 v92, v52, v84
	v_fma_f32 v68, v92, v36, v20
	v_mul_f32_e32 v93, v53, v84
	v_fma_f32 v69, v93, v37, v21
	v_mul_f32_e32 v94, v54, v84
	v_fma_f32 v70, v94, v38, v22
	v_mul_f32_e32 v95, v55, v84
	v_fma_f32 v71, v95, v39, v23
	v_mul_f32_e32 v92, v56, v84
	v_fma_f32 v72, v92, v40, v24
	v_mul_f32_e32 v93, v57, v84
	v_fma_f32 v73, v93, v41, v25
	v_mul_f32_e32 v94, v58, v84
	v_fma_f32 v74, v94, v42, v26
	v_mul_f32_e32 v95, v59, v84
	v_fma_f32 v75, v95, v43, v27
	v_mul_f32_e32 v92, v60, v84
	v_fma_f32 v76, v92, v44, v28
	v_mul_f32_e32 v93, v61, v84
	v_fma_f32 v77, v93, v45, v29
	v_mul_f32_e32 v94, v62, v84
	v_fma_f32 v78, v94, v46, v30
	v_mul_f32_e32 v95, v63, v84
	v_fma_f32 v79, v95, v47, v31
	s_add_u32 s22, s18, s21
	s_addc_u32 s23, s19, 0
	v_cvt_pk_bf16_f32 v108, v64, v65
	v_cvt_pk_bf16_f32 v109, v66, v67
	v_cvt_pk_bf16_f32 v110, v68, v69
	v_cvt_pk_bf16_f32 v111, v70, v71
	v_cvt_pk_bf16_f32 v112, v72, v73
	v_cvt_pk_bf16_f32 v113, v74, v75
	v_cvt_pk_bf16_f32 v114, v76, v77
	v_cvt_pk_bf16_f32 v115, v78, v79
	global_store_dwordx4 v82, v[108:111], s[22:23]
	global_store_dwordx4 v82, v[112:115], s[22:23] offset:1024
	s_add_u32 s20, s20, s14
	s_cmp_ge_u32 s20, 0x2800
	s_cbranch_scc1 .Lgro8_bend
	s_sub_u32 s4, s20, 0x2000
	s_lshr_b32 s4, s4, 10
	s_add_u32 s4, s4, 1
	s_cmp_lt_u32 s20, 0x2000
	s_cselect_b32 s4, 0, s4
	s_cmp_eq_u32 s4, s15
	s_cbranch_scc1 .Lgro8_r2_same
	s_mov_b32 s15, s4
	s_mul_i32 s4, s4, 0x9000
	s_add_u32 s32, s4, s6
	s_add_u32 s22, s16, s32
	s_addc_u32 s23, s17, 0
	global_load_dwordx4 v[0:3], v83, s[22:23]
	global_load_dwordx4 v[4:7], v83, s[22:23] offset:16
	global_load_dwordx4 v[8:11], v83, s[22:23] offset:2048
	global_load_dwordx4 v[12:15], v83, s[22:23] offset:2064
	s_add_u32 s32, s4, s7
	s_add_u32 s22, s16, s32
	s_addc_u32 s23, s17, 0
	global_load_dwordx4 v[16:19], v83, s[22:23]
	global_load_dwordx4 v[20:23], v83, s[22:23] offset:16
	global_load_dwordx4 v[24:27], v83, s[22:23] offset:2048
	global_load_dwordx4 v[28:31], v83, s[22:23] offset:2064
	s_add_u32 s22, s22, 0x1000
	s_addc_u32 s23, s23, 0
	global_load_dwordx4 v[32:35], v83, s[22:23]
	global_load_dwordx4 v[36:39], v83, s[22:23] offset:16
	global_load_dwordx4 v[40:43], v83, s[22:23] offset:2048
	global_load_dwordx4 v[44:47], v83, s[22:23] offset:2064
	s_waitcnt vmcnt(0)
	s_branch .Lgro8_r2_go
.Lgro8_r2_same:
	s_waitcnt vmcnt(16)
.Lgro8_r2_go:
	v_lshlrev_b32_e32 v48, 16, v200
	v_and_b32_e32 v49, 0xffff0000, v200
	v_lshlrev_b32_e32 v50, 16, v201
	v_and_b32_e32 v51, 0xffff0000, v201
	v_lshlrev_b32_e32 v52, 16, v202
	v_and_b32_e32 v53, 0xffff0000, v202
	v_lshlrev_b32_e32 v54, 16, v203
	v_and_b32_e32 v55, 0xffff0000, v203
	v_lshlrev_b32_e32 v56, 16, v204
	v_and_b32_e32 v57, 0xffff0000, v204
	v_lshlrev_b32_e32 v58, 16, v205
	v_and_b32_e32 v59, 0xffff0000, v205
	v_lshlrev_b32_e32 v60, 16, v206
	v_and_b32_e32 v61, 0xffff0000, v206
	v_lshlrev_b32_e32 v62, 16, v207
	v_and_b32_e32 v63, 0xffff0000, v207
	v_lshlrev_b32_e32 v64, 16, v208
	v_and_b32_e32 v65, 0xffff0000, v208
	v_lshlrev_b32_e32 v66, 16, v209
	v_and_b32_e32 v67, 0xffff0000, v209
	v_lshlrev_b32_e32 v68, 16, v210
	v_and_b32_e32 v69, 0xffff0000, v210
	v_lshlrev_b32_e32 v70, 16, v211
	v_and_b32_e32 v71, 0xffff0000, v211
	v_lshlrev_b32_e32 v72, 16, v212
	v_and_b32_e32 v73, 0xffff0000, v212
	v_lshlrev_b32_e32 v74, 16, v213
	v_and_b32_e32 v75, 0xffff0000, v213
	v_lshlrev_b32_e32 v76, 16, v214
	v_and_b32_e32 v77, 0xffff0000, v214
	v_lshlrev_b32_e32 v78, 16, v215
	v_and_b32_e32 v79, 0xffff0000, v215
	v_mul_f32_e32 v88, v64, v64
	v_mul_f32_e32 v89, v65, v65
	v_mul_f32_e32 v90, v66, v66
	v_mul_f32_e32 v91, v67, v67
	v_fmac_f32_e32 v88, v68, v68
	v_fmac_f32_e32 v89, v69, v69
	v_fmac_f32_e32 v90, v70, v70
	v_fmac_f32_e32 v91, v71, v71
	v_fmac_f32_e32 v88, v72, v72
	v_fmac_f32_e32 v89, v73, v73
	v_fmac_f32_e32 v90, v74, v74
	v_fmac_f32_e32 v91, v75, v75
	v_fmac_f32_e32 v88, v76, v76
	v_fmac_f32_e32 v89, v77, v77
	v_fmac_f32_e32 v90, v78, v78
	v_fmac_f32_e32 v91, v79, v79
	v_add_f32_e32 v88, v88, v89
	v_add_f32_e32 v90, v90, v91
	v_add_f32_e32 v84, v88, v90
	s_nop 1
	v_add_f32_dpp v84, v84, v84 quad_perm:[1,0,3,2] row_mask:0xf bank_mask:0xf bound_ctrl:1
	s_nop 1
	v_add_f32_dpp v84, v84, v84 quad_perm:[2,3,0,1] row_mask:0xf bank_mask:0xf bound_ctrl:1
	s_nop 1
	v_add_f32_dpp v84, v84, v84 row_half_mirror row_mask:0xf bank_mask:0xf bound_ctrl:1
	s_nop 1
	v_add_f32_dpp v84, v84, v84 row_mirror row_mask:0xf bank_mask:0xf bound_ctrl:1
	s_nop 0
	v_readlane_b32 s44, v84, 0
	v_readlane_b32 s46, v84, 16
	v_readlane_b32 s48, v84, 32
	v_readlane_b32 s50, v84, 48
	s_nop 0
	v_mov_b32_e32 v85, s44
	v_mov_b32_e32 v86, s48
	v_add_f32_e32 v85, s46, v85
	v_add_f32_e32 v86, s50, v86
	v_add_f32_e32 v84, v85, v86
	v_fmamk_f32 v84, v84, 0x3a800000, v130
	v_rsq_f32_e32 v84, v84
	s_nop 0
	v_mul_f32_e32 v92, v84, v64
	v_fmac_f32_e32 v48, v0, v92
	v_mul_f32_e32 v93, v84, v65
	v_fmac_f32_e32 v49, v1, v93
	v_mul_f32_e32 v94, v84, v66
	v_fmac_f32_e32 v50, v2, v94
	v_mul_f32_e32 v95, v84, v67
	v_fmac_f32_e32 v51, v3, v95
	v_mul_f32_e32 v92, v84, v68
	v_fmac_f32_e32 v52, v4, v92
	v_mul_f32_e32 v93, v84, v69
	v_fmac_f32_e32 v53, v5, v93
	v_mul_f32_e32 v94, v84, v70
	v_fmac_f32_e32 v54, v6, v94
	v_mul_f32_e32 v95, v84, v71
	v_fmac_f32_e32 v55, v7, v95
	v_mul_f32_e32 v92, v84, v72
	v_fmac_f32_e32 v56, v8, v92
	v_mul_f32_e32 v93, v84, v73
	v_fmac_f32_e32 v57, v9, v93
	v_mul_f32_e32 v94, v84, v74
	v_fmac_f32_e32 v58, v10, v94
	v_mul_f32_e32 v95, v84, v75
	v_fmac_f32_e32 v59, v11, v95
	v_mul_f32_e32 v92, v84, v76
	v_fmac_f32_e32 v60, v12, v92
	v_mul_f32_e32 v93, v84, v77
	v_fmac_f32_e32 v61, v13, v93
	v_mul_f32_e32 v94, v84, v78
	v_fmac_f32_e32 v62, v14, v94
	v_mul_f32_e32 v95, v84, v79
	v_fmac_f32_e32 v63, v15, v95
	s_lshl_b32 s21, s20, 11
	s_add_u32 s22, s86, s21
	s_addc_u32 s23, s87, 0
	v_cvt_pk_bf16_f32 v100, v48, v49
	v_cvt_pk_bf16_f32 v101, v50, v51
	v_cvt_pk_bf16_f32 v102, v52, v53
	v_cvt_pk_bf16_f32 v103, v54, v55
	v_cvt_pk_bf16_f32 v104, v56, v57
	v_cvt_pk_bf16_f32 v105, v58, v59
	v_cvt_pk_bf16_f32 v106, v60, v61
	v_cvt_pk_bf16_f32 v107, v62, v63
	global_store_dwordx4 v82, v[100:103], s[22:23]
	global_store_dwordx4 v82, v[104:107], s[22:23] offset:1024
	v_mul_f32_e32 v88, v48, v48
	v_mul_f32_e32 v89, v49, v49
	v_mul_f32_e32 v90, v50, v50
	v_mul_f32_e32 v91, v51, v51
	v_fmac_f32_e32 v88, v52, v52
	v_fmac_f32_e32 v89, v53, v53
	v_fmac_f32_e32 v90, v54, v54
	v_fmac_f32_e32 v91, v55, v55
	v_fmac_f32_e32 v88, v56, v56
	v_fmac_f32_e32 v89, v57, v57
	v_fmac_f32_e32 v90, v58, v58
	v_fmac_f32_e32 v91, v59, v59
	v_fmac_f32_e32 v88, v60, v60
	v_fmac_f32_e32 v89, v61, v61
	v_fmac_f32_e32 v90, v62, v62
	v_fmac_f32_e32 v91, v63, v63
	v_add_f32_e32 v88, v88, v89
	v_add_f32_e32 v90, v90, v91
	v_add_f32_e32 v84, v88, v90
	s_nop 1
	v_add_f32_dpp v84, v84, v84 quad_perm:[1,0,3,2] row_mask:0xf bank_mask:0xf bound_ctrl:1
	s_nop 1
	v_add_f32_dpp v84, v84, v84 quad_perm:[2,3,0,1] row_mask:0xf bank_mask:0xf bound_ctrl:1
	s_nop 1
	v_add_f32_dpp v84, v84, v84 row_half_mirror row_mask:0xf bank_mask:0xf bound_ctrl:1
	s_nop 1
	v_add_f32_dpp v84, v84, v84 row_mirror row_mask:0xf bank_mask:0xf bound_ctrl:1
	s_nop 0
	v_readlane_b32 s44, v84, 0
	v_readlane_b32 s46, v84, 16
	v_readlane_b32 s48, v84, 32
	v_readlane_b32 s50, v84, 48
	s_nop 0
	v_mov_b32_e32 v85, s44
	v_mov_b32_e32 v86, s48
	v_add_f32_e32 v85, s46, v85
	v_add_f32_e32 v86, s50, v86
	v_add_f32_e32 v84, v85, v86
	v_fmamk_f32 v84, v84, 0x3a800000, v130
	v_rsq_f32_e32 v84, v84
	s_nop 0
	v_mul_f32_e32 v92, v48, v84
	v_fma_f32 v64, v92, v32, v16
	v_mul_f32_e32 v93, v49, v84
	v_fma_f32 v65, v93, v33, v17
	v_mul_f32_e32 v94, v50, v84
	v_fma_f32 v66, v94, v34, v18
	v_mul_f32_e32 v95, v51, v84
	v_fma_f32 v67, v95, v35, v19
	v_mul_f32_e32 v92, v52, v84
	v_fma_f32 v68, v92, v36, v20
	v_mul_f32_e32 v93, v53, v84
	v_fma_f32 v69, v93, v37, v21
	v_mul_f32_e32 v94, v54, v84
	v_fma_f32 v70, v94, v38, v22
	v_mul_f32_e32 v95, v55, v84
	v_fma_f32 v71, v95, v39, v23
	v_mul_f32_e32 v92, v56, v84
	v_fma_f32 v72, v92, v40, v24
	v_mul_f32_e32 v93, v57, v84
	v_fma_f32 v73, v93, v41, v25
	v_mul_f32_e32 v94, v58, v84
	v_fma_f32 v74, v94, v42, v26
	v_mul_f32_e32 v95, v59, v84
	v_fma_f32 v75, v95, v43, v27
	v_mul_f32_e32 v92, v60, v84
	v_fma_f32 v76, v92, v44, v28
	v_mul_f32_e32 v93, v61, v84
	v_fma_f32 v77, v93, v45, v29
	v_mul_f32_e32 v94, v62, v84
	v_fma_f32 v78, v94, v46, v30
	v_mul_f32_e32 v95, v63, v84
	v_fma_f32 v79, v95, v47, v31
	s_add_u32 s22, s18, s21
	s_addc_u32 s23, s19, 0
	v_cvt_pk_bf16_f32 v108, v64, v65
	v_cvt_pk_bf16_f32 v109, v66, v67
	v_cvt_pk_bf16_f32 v110, v68, v69
	v_cvt_pk_bf16_f32 v111, v70, v71
	v_cvt_pk_bf16_f32 v112, v72, v73
	v_cvt_pk_bf16_f32 v113, v74, v75
	v_cvt_pk_bf16_f32 v114, v76, v77
	v_cvt_pk_bf16_f32 v115, v78, v79
	global_store_dwordx4 v82, v[108:111], s[22:23]
	global_store_dwordx4 v82, v[112:115], s[22:23] offset:1024
	s_add_u32 s20, s20, s14
	s_cmp_ge_u32 s20, 0x2800
	s_cbranch_scc1 .Lgro8_bend
	s_sub_u32 s4, s20, 0x2000
	s_lshr_b32 s4, s4, 10
	s_add_u32 s4, s4, 1
	s_cmp_lt_u32 s20, 0x2000
	s_cselect_b32 s4, 0, s4
	s_cmp_eq_u32 s4, s15
	s_cbranch_scc1 .Lgro8_r3_same
	s_mov_b32 s15, s4
	s_mul_i32 s4, s4, 0x9000
	s_add_u32 s32, s4, s6
	s_add_u32 s22, s16, s32
	s_addc_u32 s23, s17, 0
	global_load_dwordx4 v[0:3], v83, s[22:23]
	global_load_dwordx4 v[4:7], v83, s[22:23] offset:16
	global_load_dwordx4 v[8:11], v83, s[22:23] offset:2048
	global_load_dwordx4 v[12:15], v83, s[22:23] offset:2064
	s_add_u32 s32, s4, s7
	s_add_u32 s22, s16, s32
	s_addc_u32 s23, s17, 0
	global_load_dwordx4 v[16:19], v83, s[22:23]
	global_load_dwordx4 v[20:23], v83, s[22:23] offset:16
	global_load_dwordx4 v[24:27], v83, s[22:23] offset:2048
	global_load_dwordx4 v[28:31], v83, s[22:23] offset:2064
	s_add_u32 s22, s22, 0x1000
	s_addc_u32 s23, s23, 0
	global_load_dwordx4 v[32:35], v83, s[22:23]
	global_load_dwordx4 v[36:39], v83, s[22:23] offset:16
	global_load_dwordx4 v[40:43], v83, s[22:23] offset:2048
	global_load_dwordx4 v[44:47], v83, s[22:23] offset:2064
	s_waitcnt vmcnt(0)
	s_branch .Lgro8_r3_go
.Lgro8_r3_same:
	s_waitcnt vmcnt(16)
.Lgro8_r3_go:
	v_lshlrev_b32_e32 v48, 16, v216
	v_and_b32_e32 v49, 0xffff0000, v216
	v_lshlrev_b32_e32 v50, 16, v217
	v_and_b32_e32 v51, 0xffff0000, v217
	v_lshlrev_b32_e32 v52, 16, v218
	v_and_b32_e32 v53, 0xffff0000, v218
	v_lshlrev_b32_e32 v54, 16, v219
	v_and_b32_e32 v55, 0xffff0000, v219
	v_lshlrev_b32_e32 v56, 16, v220
	v_and_b32_e32 v57, 0xffff0000, v220
	v_lshlrev_b32_e32 v58, 16, v221
	v_and_b32_e32 v59, 0xffff0000, v221
	v_lshlrev_b32_e32 v60, 16, v222
	v_and_b32_e32 v61, 0xffff0000, v222
	v_lshlrev_b32_e32 v62, 16, v223
	v_and_b32_e32 v63, 0xffff0000, v223
	v_lshlrev_b32_e32 v64, 16, v224
	v_and_b32_e32 v65, 0xffff0000, v224
	v_lshlrev_b32_e32 v66, 16, v225
	v_and_b32_e32 v67, 0xffff0000, v225
	v_lshlrev_b32_e32 v68, 16, v226
	v_and_b32_e32 v69, 0xffff0000, v226
	v_lshlrev_b32_e32 v70, 16, v227
	v_and_b32_e32 v71, 0xffff0000, v227
	v_lshlrev_b32_e32 v72, 16, v228
	v_and_b32_e32 v73, 0xffff0000, v228
	v_lshlrev_b32_e32 v74, 16, v229
	v_and_b32_e32 v75, 0xffff0000, v229
	v_lshlrev_b32_e32 v76, 16, v230
	v_and_b32_e32 v77, 0xffff0000, v230
	v_lshlrev_b32_e32 v78, 16, v231
	v_and_b32_e32 v79, 0xffff0000, v231
	v_mul_f32_e32 v88, v64, v64
	v_mul_f32_e32 v89, v65, v65
	v_mul_f32_e32 v90, v66, v66
	v_mul_f32_e32 v91, v67, v67
	v_fmac_f32_e32 v88, v68, v68
	v_fmac_f32_e32 v89, v69, v69
	v_fmac_f32_e32 v90, v70, v70
	v_fmac_f32_e32 v91, v71, v71
	v_fmac_f32_e32 v88, v72, v72
	v_fmac_f32_e32 v89, v73, v73
	v_fmac_f32_e32 v90, v74, v74
	v_fmac_f32_e32 v91, v75, v75
	v_fmac_f32_e32 v88, v76, v76
	v_fmac_f32_e32 v89, v77, v77
	v_fmac_f32_e32 v90, v78, v78
	v_fmac_f32_e32 v91, v79, v79
	v_add_f32_e32 v88, v88, v89
	v_add_f32_e32 v90, v90, v91
	v_add_f32_e32 v84, v88, v90
	s_nop 1
	v_add_f32_dpp v84, v84, v84 quad_perm:[1,0,3,2] row_mask:0xf bank_mask:0xf bound_ctrl:1
	s_nop 1
	v_add_f32_dpp v84, v84, v84 quad_perm:[2,3,0,1] row_mask:0xf bank_mask:0xf bound_ctrl:1
	s_nop 1
	v_add_f32_dpp v84, v84, v84 row_half_mirror row_mask:0xf bank_mask:0xf bound_ctrl:1
	s_nop 1
	v_add_f32_dpp v84, v84, v84 row_mirror row_mask:0xf bank_mask:0xf bound_ctrl:1
	s_nop 0
	v_readlane_b32 s44, v84, 0
	v_readlane_b32 s46, v84, 16
	v_readlane_b32 s48, v84, 32
	v_readlane_b32 s50, v84, 48
	s_nop 0
	v_mov_b32_e32 v85, s44
	v_mov_b32_e32 v86, s48
	v_add_f32_e32 v85, s46, v85
	v_add_f32_e32 v86, s50, v86
	v_add_f32_e32 v84, v85, v86
	v_fmamk_f32 v84, v84, 0x3a800000, v130
	v_rsq_f32_e32 v84, v84
	s_nop 0
	v_mul_f32_e32 v92, v84, v64
	v_fmac_f32_e32 v48, v0, v92
	v_mul_f32_e32 v93, v84, v65
	v_fmac_f32_e32 v49, v1, v93
	v_mul_f32_e32 v94, v84, v66
	v_fmac_f32_e32 v50, v2, v94
	v_mul_f32_e32 v95, v84, v67
	v_fmac_f32_e32 v51, v3, v95
	v_mul_f32_e32 v92, v84, v68
	v_fmac_f32_e32 v52, v4, v92
	v_mul_f32_e32 v93, v84, v69
	v_fmac_f32_e32 v53, v5, v93
	v_mul_f32_e32 v94, v84, v70
	v_fmac_f32_e32 v54, v6, v94
	v_mul_f32_e32 v95, v84, v71
	v_fmac_f32_e32 v55, v7, v95
	v_mul_f32_e32 v92, v84, v72
	v_fmac_f32_e32 v56, v8, v92
	v_mul_f32_e32 v93, v84, v73
	v_fmac_f32_e32 v57, v9, v93
	v_mul_f32_e32 v94, v84, v74
	v_fmac_f32_e32 v58, v10, v94
	v_mul_f32_e32 v95, v84, v75
	v_fmac_f32_e32 v59, v11, v95
	v_mul_f32_e32 v92, v84, v76
	v_fmac_f32_e32 v60, v12, v92
	v_mul_f32_e32 v93, v84, v77
	v_fmac_f32_e32 v61, v13, v93
	v_mul_f32_e32 v94, v84, v78
	v_fmac_f32_e32 v62, v14, v94
	v_mul_f32_e32 v95, v84, v79
	v_fmac_f32_e32 v63, v15, v95
	s_lshl_b32 s21, s20, 11
	s_add_u32 s22, s86, s21
	s_addc_u32 s23, s87, 0
	v_cvt_pk_bf16_f32 v100, v48, v49
	v_cvt_pk_bf16_f32 v101, v50, v51
	v_cvt_pk_bf16_f32 v102, v52, v53
	v_cvt_pk_bf16_f32 v103, v54, v55
	v_cvt_pk_bf16_f32 v104, v56, v57
	v_cvt_pk_bf16_f32 v105, v58, v59
	v_cvt_pk_bf16_f32 v106, v60, v61
	v_cvt_pk_bf16_f32 v107, v62, v63
	global_store_dwordx4 v82, v[100:103], s[22:23]
	global_store_dwordx4 v82, v[104:107], s[22:23] offset:1024
	v_mul_f32_e32 v88, v48, v48
	v_mul_f32_e32 v89, v49, v49
	v_mul_f32_e32 v90, v50, v50
	v_mul_f32_e32 v91, v51, v51
	v_fmac_f32_e32 v88, v52, v52
	v_fmac_f32_e32 v89, v53, v53
	v_fmac_f32_e32 v90, v54, v54
	v_fmac_f32_e32 v91, v55, v55
	v_fmac_f32_e32 v88, v56, v56
	v_fmac_f32_e32 v89, v57, v57
	v_fmac_f32_e32 v90, v58, v58
	v_fmac_f32_e32 v91, v59, v59
	v_fmac_f32_e32 v88, v60, v60
	v_fmac_f32_e32 v89, v61, v61
	v_fmac_f32_e32 v90, v62, v62
	v_fmac_f32_e32 v91, v63, v63
	v_add_f32_e32 v88, v88, v89
	v_add_f32_e32 v90, v90, v91
	v_add_f32_e32 v84, v88, v90
	s_nop 1
	v_add_f32_dpp v84, v84, v84 quad_perm:[1,0,3,2] row_mask:0xf bank_mask:0xf bound_ctrl:1
	s_nop 1
	v_add_f32_dpp v84, v84, v84 quad_perm:[2,3,0,1] row_mask:0xf bank_mask:0xf bound_ctrl:1
	s_nop 1
	v_add_f32_dpp v84, v84, v84 row_half_mirror row_mask:0xf bank_mask:0xf bound_ctrl:1
	s_nop 1
	v_add_f32_dpp v84, v84, v84 row_mirror row_mask:0xf bank_mask:0xf bound_ctrl:1
	s_nop 0
	v_readlane_b32 s44, v84, 0
	v_readlane_b32 s46, v84, 16
	v_readlane_b32 s48, v84, 32
	v_readlane_b32 s50, v84, 48
	s_nop 0
	v_mov_b32_e32 v85, s44
	v_mov_b32_e32 v86, s48
	v_add_f32_e32 v85, s46, v85
	v_add_f32_e32 v86, s50, v86
	v_add_f32_e32 v84, v85, v86
	v_fmamk_f32 v84, v84, 0x3a800000, v130
	v_rsq_f32_e32 v84, v84
	s_nop 0
	v_mul_f32_e32 v92, v48, v84
	v_fma_f32 v64, v92, v32, v16
	v_mul_f32_e32 v93, v49, v84
	v_fma_f32 v65, v93, v33, v17
	v_mul_f32_e32 v94, v50, v84
	v_fma_f32 v66, v94, v34, v18
	v_mul_f32_e32 v95, v51, v84
	v_fma_f32 v67, v95, v35, v19
	v_mul_f32_e32 v92, v52, v84
	v_fma_f32 v68, v92, v36, v20
	v_mul_f32_e32 v93, v53, v84
	v_fma_f32 v69, v93, v37, v21
	v_mul_f32_e32 v94, v54, v84
	v_fma_f32 v70, v94, v38, v22
	v_mul_f32_e32 v95, v55, v84
	v_fma_f32 v71, v95, v39, v23
	v_mul_f32_e32 v92, v56, v84
	v_fma_f32 v72, v92, v40, v24
	v_mul_f32_e32 v93, v57, v84
	v_fma_f32 v73, v93, v41, v25
	v_mul_f32_e32 v94, v58, v84
	v_fma_f32 v74, v94, v42, v26
	v_mul_f32_e32 v95, v59, v84
	v_fma_f32 v75, v95, v43, v27
	v_mul_f32_e32 v92, v60, v84
	v_fma_f32 v76, v92, v44, v28
	v_mul_f32_e32 v93, v61, v84
	v_fma_f32 v77, v93, v45, v29
	v_mul_f32_e32 v94, v62, v84
	v_fma_f32 v78, v94, v46, v30
	v_mul_f32_e32 v95, v63, v84
	v_fma_f32 v79, v95, v47, v31
	s_add_u32 s22, s18, s21
	s_addc_u32 s23, s19, 0
	v_cvt_pk_bf16_f32 v108, v64, v65
	v_cvt_pk_bf16_f32 v109, v66, v67
	v_cvt_pk_bf16_f32 v110, v68, v69
	v_cvt_pk_bf16_f32 v111, v70, v71
	v_cvt_pk_bf16_f32 v112, v72, v73
	v_cvt_pk_bf16_f32 v113, v74, v75
	v_cvt_pk_bf16_f32 v114, v76, v77
	v_cvt_pk_bf16_f32 v115, v78, v79
	global_store_dwordx4 v82, v[108:111], s[22:23]
	global_store_dwordx4 v82, v[112:115], s[22:23] offset:1024
	s_add_u32 s20, s20, s14
	s_cmp_ge_u32 s20, 0x2800
	s_cbranch_scc1 .Lgro8_bend
	s_sub_u32 s4, s20, 0x2000
	s_lshr_b32 s4, s4, 10
	s_add_u32 s4, s4, 1
	s_cmp_lt_u32 s20, 0x2000
	s_cselect_b32 s4, 0, s4
	s_cmp_eq_u32 s4, s15
	s_cbranch_scc1 .Lgro8_r4_same
	s_mov_b32 s15, s4
	s_mul_i32 s4, s4, 0x9000
	s_add_u32 s32, s4, s6
	s_add_u32 s22, s16, s32
	s_addc_u32 s23, s17, 0
	global_load_dwordx4 v[0:3], v83, s[22:23]
	global_load_dwordx4 v[4:7], v83, s[22:23] offset:16
	global_load_dwordx4 v[8:11], v83, s[22:23] offset:2048
	global_load_dwordx4 v[12:15], v83, s[22:23] offset:2064
	s_add_u32 s32, s4, s7
	s_add_u32 s22, s16, s32
	s_addc_u32 s23, s17, 0
	global_load_dwordx4 v[16:19], v83, s[22:23]
	global_load_dwordx4 v[20:23], v83, s[22:23] offset:16
	global_load_dwordx4 v[24:27], v83, s[22:23] offset:2048
	global_load_dwordx4 v[28:31], v83, s[22:23] offset:2064
	s_add_u32 s22, s22, 0x1000
	s_addc_u32 s23, s23, 0
	global_load_dwordx4 v[32:35], v83, s[22:23]
	global_load_dwordx4 v[36:39], v83, s[22:23] offset:16
	global_load_dwordx4 v[40:43], v83, s[22:23] offset:2048
	global_load_dwordx4 v[44:47], v83, s[22:23] offset:2064
	s_waitcnt vmcnt(0)
	s_branch .Lgro8_r4_go
.Lgro8_r4_same:
	s_waitcnt vmcnt(16)
.Lgro8_r4_go:
	v_lshlrev_b32_e32 v48, 16, v232
	v_and_b32_e32 v49, 0xffff0000, v232
	v_lshlrev_b32_e32 v50, 16, v233
	v_and_b32_e32 v51, 0xffff0000, v233
	v_lshlrev_b32_e32 v52, 16, v234
	v_and_b32_e32 v53, 0xffff0000, v234
	v_lshlrev_b32_e32 v54, 16, v235
	v_and_b32_e32 v55, 0xffff0000, v235
	v_lshlrev_b32_e32 v56, 16, v236
	v_and_b32_e32 v57, 0xffff0000, v236
	v_lshlrev_b32_e32 v58, 16, v237
	v_and_b32_e32 v59, 0xffff0000, v237
	v_lshlrev_b32_e32 v60, 16, v238
	v_and_b32_e32 v61, 0xffff0000, v238
	v_lshlrev_b32_e32 v62, 16, v239
	v_and_b32_e32 v63, 0xffff0000, v239
	v_lshlrev_b32_e32 v64, 16, v240
	v_and_b32_e32 v65, 0xffff0000, v240
	v_lshlrev_b32_e32 v66, 16, v241
	v_and_b32_e32 v67, 0xffff0000, v241
	v_lshlrev_b32_e32 v68, 16, v242
	v_and_b32_e32 v69, 0xffff0000, v242
	v_lshlrev_b32_e32 v70, 16, v243
	v_and_b32_e32 v71, 0xffff0000, v243
	v_lshlrev_b32_e32 v72, 16, v244
	v_and_b32_e32 v73, 0xffff0000, v244
	v_lshlrev_b32_e32 v74, 16, v245
	v_and_b32_e32 v75, 0xffff0000, v245
	v_lshlrev_b32_e32 v76, 16, v246
	v_and_b32_e32 v77, 0xffff0000, v246
	v_lshlrev_b32_e32 v78, 16, v247
	v_and_b32_e32 v79, 0xffff0000, v247
	v_mul_f32_e32 v88, v64, v64
	v_mul_f32_e32 v89, v65, v65
	v_mul_f32_e32 v90, v66, v66
	v_mul_f32_e32 v91, v67, v67
	v_fmac_f32_e32 v88, v68, v68
	v_fmac_f32_e32 v89, v69, v69
	v_fmac_f32_e32 v90, v70, v70
	v_fmac_f32_e32 v91, v71, v71
	v_fmac_f32_e32 v88, v72, v72
	v_fmac_f32_e32 v89, v73, v73
	v_fmac_f32_e32 v90, v74, v74
	v_fmac_f32_e32 v91, v75, v75
	v_fmac_f32_e32 v88, v76, v76
	v_fmac_f32_e32 v89, v77, v77
	v_fmac_f32_e32 v90, v78, v78
	v_fmac_f32_e32 v91, v79, v79
	v_add_f32_e32 v88, v88, v89
	v_add_f32_e32 v90, v90, v91
	v_add_f32_e32 v84, v88, v90
	s_nop 1
	v_add_f32_dpp v84, v84, v84 quad_perm:[1,0,3,2] row_mask:0xf bank_mask:0xf bound_ctrl:1
	s_nop 1
	v_add_f32_dpp v84, v84, v84 quad_perm:[2,3,0,1] row_mask:0xf bank_mask:0xf bound_ctrl:1
	s_nop 1
	v_add_f32_dpp v84, v84, v84 row_half_mirror row_mask:0xf bank_mask:0xf bound_ctrl:1
	s_nop 1
	v_add_f32_dpp v84, v84, v84 row_mirror row_mask:0xf bank_mask:0xf bound_ctrl:1
	s_nop 0
	v_readlane_b32 s44, v84, 0
	v_readlane_b32 s46, v84, 16
	v_readlane_b32 s48, v84, 32
	v_readlane_b32 s50, v84, 48
	s_nop 0
	v_mov_b32_e32 v85, s44
	v_mov_b32_e32 v86, s48
	v_add_f32_e32 v85, s46, v85
	v_add_f32_e32 v86, s50, v86
	v_add_f32_e32 v84, v85, v86
	v_fmamk_f32 v84, v84, 0x3a800000, v130
	v_rsq_f32_e32 v84, v84
	s_nop 0
	v_mul_f32_e32 v92, v84, v64
	v_fmac_f32_e32 v48, v0, v92
	v_mul_f32_e32 v93, v84, v65
	v_fmac_f32_e32 v49, v1, v93
	v_mul_f32_e32 v94, v84, v66
	v_fmac_f32_e32 v50, v2, v94
	v_mul_f32_e32 v95, v84, v67
	v_fmac_f32_e32 v51, v3, v95
	v_mul_f32_e32 v92, v84, v68
	v_fmac_f32_e32 v52, v4, v92
	v_mul_f32_e32 v93, v84, v69
	v_fmac_f32_e32 v53, v5, v93
	v_mul_f32_e32 v94, v84, v70
	v_fmac_f32_e32 v54, v6, v94
	v_mul_f32_e32 v95, v84, v71
	v_fmac_f32_e32 v55, v7, v95
	v_mul_f32_e32 v92, v84, v72
	v_fmac_f32_e32 v56, v8, v92
	v_mul_f32_e32 v93, v84, v73
	v_fmac_f32_e32 v57, v9, v93
	v_mul_f32_e32 v94, v84, v74
	v_fmac_f32_e32 v58, v10, v94
	v_mul_f32_e32 v95, v84, v75
	v_fmac_f32_e32 v59, v11, v95
	v_mul_f32_e32 v92, v84, v76
	v_fmac_f32_e32 v60, v12, v92
	v_mul_f32_e32 v93, v84, v77
	v_fmac_f32_e32 v61, v13, v93
	v_mul_f32_e32 v94, v84, v78
	v_fmac_f32_e32 v62, v14, v94
	v_mul_f32_e32 v95, v84, v79
	v_fmac_f32_e32 v63, v15, v95
	s_lshl_b32 s21, s20, 11
	s_add_u32 s22, s86, s21
	s_addc_u32 s23, s87, 0
	v_cvt_pk_bf16_f32 v100, v48, v49
	v_cvt_pk_bf16_f32 v101, v50, v51
	v_cvt_pk_bf16_f32 v102, v52, v53
	v_cvt_pk_bf16_f32 v103, v54, v55
	v_cvt_pk_bf16_f32 v104, v56, v57
	v_cvt_pk_bf16_f32 v105, v58, v59
	v_cvt_pk_bf16_f32 v106, v60, v61
	v_cvt_pk_bf16_f32 v107, v62, v63
	global_store_dwordx4 v82, v[100:103], s[22:23]
	global_store_dwordx4 v82, v[104:107], s[22:23] offset:1024
	v_mul_f32_e32 v88, v48, v48
	v_mul_f32_e32 v89, v49, v49
	v_mul_f32_e32 v90, v50, v50
	v_mul_f32_e32 v91, v51, v51
	v_fmac_f32_e32 v88, v52, v52
	v_fmac_f32_e32 v89, v53, v53
	v_fmac_f32_e32 v90, v54, v54
	v_fmac_f32_e32 v91, v55, v55
	v_fmac_f32_e32 v88, v56, v56
	v_fmac_f32_e32 v89, v57, v57
	v_fmac_f32_e32 v90, v58, v58
	v_fmac_f32_e32 v91, v59, v59
	v_fmac_f32_e32 v88, v60, v60
	v_fmac_f32_e32 v89, v61, v61
	v_fmac_f32_e32 v90, v62, v62
	v_fmac_f32_e32 v91, v63, v63
	v_add_f32_e32 v88, v88, v89
	v_add_f32_e32 v90, v90, v91
	v_add_f32_e32 v84, v88, v90
	s_nop 1
	v_add_f32_dpp v84, v84, v84 quad_perm:[1,0,3,2] row_mask:0xf bank_mask:0xf bound_ctrl:1
	s_nop 1
	v_add_f32_dpp v84, v84, v84 quad_perm:[2,3,0,1] row_mask:0xf bank_mask:0xf bound_ctrl:1
	s_nop 1
	v_add_f32_dpp v84, v84, v84 row_half_mirror row_mask:0xf bank_mask:0xf bound_ctrl:1
	s_nop 1
	v_add_f32_dpp v84, v84, v84 row_mirror row_mask:0xf bank_mask:0xf bound_ctrl:1
	s_nop 0
	v_readlane_b32 s44, v84, 0
	v_readlane_b32 s46, v84, 16
	v_readlane_b32 s48, v84, 32
	v_readlane_b32 s50, v84, 48
	s_nop 0
	v_mov_b32_e32 v85, s44
	v_mov_b32_e32 v86, s48
	v_add_f32_e32 v85, s46, v85
	v_add_f32_e32 v86, s50, v86
	v_add_f32_e32 v84, v85, v86
	v_fmamk_f32 v84, v84, 0x3a800000, v130
	v_rsq_f32_e32 v84, v84
	s_nop 0
	v_mul_f32_e32 v92, v48, v84
	v_fma_f32 v64, v92, v32, v16
	v_mul_f32_e32 v93, v49, v84
	v_fma_f32 v65, v93, v33, v17
	v_mul_f32_e32 v94, v50, v84
	v_fma_f32 v66, v94, v34, v18
	v_mul_f32_e32 v95, v51, v84
	v_fma_f32 v67, v95, v35, v19
	v_mul_f32_e32 v92, v52, v84
	v_fma_f32 v68, v92, v36, v20
	v_mul_f32_e32 v93, v53, v84
	v_fma_f32 v69, v93, v37, v21
	v_mul_f32_e32 v94, v54, v84
	v_fma_f32 v70, v94, v38, v22
	v_mul_f32_e32 v95, v55, v84
	v_fma_f32 v71, v95, v39, v23
	v_mul_f32_e32 v92, v56, v84
	v_fma_f32 v72, v92, v40, v24
	v_mul_f32_e32 v93, v57, v84
	v_fma_f32 v73, v93, v41, v25
	v_mul_f32_e32 v94, v58, v84
	v_fma_f32 v74, v94, v42, v26
	v_mul_f32_e32 v95, v59, v84
	v_fma_f32 v75, v95, v43, v27
	v_mul_f32_e32 v92, v60, v84
	v_fma_f32 v76, v92, v44, v28
	v_mul_f32_e32 v93, v61, v84
	v_fma_f32 v77, v93, v45, v29
	v_mul_f32_e32 v94, v62, v84
	v_fma_f32 v78, v94, v46, v30
	v_mul_f32_e32 v95, v63, v84
	v_fma_f32 v79, v95, v47, v31
	s_add_u32 s22, s18, s21
	s_addc_u32 s23, s19, 0
	v_cvt_pk_bf16_f32 v108, v64, v65
	v_cvt_pk_bf16_f32 v109, v66, v67
	v_cvt_pk_bf16_f32 v110, v68, v69
	v_cvt_pk_bf16_f32 v111, v70, v71
	v_cvt_pk_bf16_f32 v112, v72, v73
	v_cvt_pk_bf16_f32 v113, v74, v75
	v_cvt_pk_bf16_f32 v114, v76, v77
	v_cvt_pk_bf16_f32 v115, v78, v79
	global_store_dwordx4 v82, v[108:111], s[22:23]
	global_store_dwordx4 v82, v[112:115], s[22:23] offset:1024

.Lgro11_r1_same:
	s_waitcnt vmcnt(16)
.Lgro11_r1_go:
	v_lshlrev_b32_e32 v48, 16, v184
	v_and_b32_e32 v49, 0xffff0000, v184
	v_lshlrev_b32_e32 v50, 16, v185
	v_and_b32_e32 v51, 0xffff0000, v185
	v_lshlrev_b32_e32 v52, 16, v186
	v_and_b32_e32 v53, 0xffff0000, v186
	v_lshlrev_b32_e32 v54, 16, v187
	v_and_b32_e32 v55, 0xffff0000, v187
	v_lshlrev_b32_e32 v56, 16, v188
	v_and_b32_e32 v57, 0xffff0000, v188
	v_lshlrev_b32_e32 v58, 16, v189
	v_and_b32_e32 v59, 0xffff0000, v189
	v_lshlrev_b32_e32 v60, 16, v190
	v_and_b32_e32 v61, 0xffff0000, v190
	v_lshlrev_b32_e32 v62, 16, v191
	v_and_b32_e32 v63, 0xffff0000, v191
	v_lshlrev_b32_e32 v64, 16, v192
	v_and_b32_e32 v65, 0xffff0000, v192
	v_lshlrev_b32_e32 v66, 16, v193
	v_and_b32_e32 v67, 0xffff0000, v193
	v_lshlrev_b32_e32 v68, 16, v194
	v_and_b32_e32 v69, 0xffff0000, v194
	v_lshlrev_b32_e32 v70, 16, v195
	v_and_b32_e32 v71, 0xffff0000, v195
	v_lshlrev_b32_e32 v72, 16, v196
	v_and_b32_e32 v73, 0xffff0000, v196
	v_lshlrev_b32_e32 v74, 16, v197
	v_and_b32_e32 v75, 0xffff0000, v197
	v_lshlrev_b32_e32 v76, 16, v198
	v_and_b32_e32 v77, 0xffff0000, v198
	v_lshlrev_b32_e32 v78, 16, v199
	v_and_b32_e32 v79, 0xffff0000, v199
	v_mul_f32_e32 v88, v64, v64
	v_mul_f32_e32 v89, v65, v65
	v_mul_f32_e32 v90, v66, v66
	v_mul_f32_e32 v91, v67, v67
	v_fmac_f32_e32 v88, v68, v68
	v_fmac_f32_e32 v89, v69, v69
	v_fmac_f32_e32 v90, v70, v70
	v_fmac_f32_e32 v91, v71, v71
	v_fmac_f32_e32 v88, v72, v72
	v_fmac_f32_e32 v89, v73, v73
	v_fmac_f32_e32 v90, v74, v74
	v_fmac_f32_e32 v91, v75, v75
	v_fmac_f32_e32 v88, v76, v76
	v_fmac_f32_e32 v89, v77, v77
	v_fmac_f32_e32 v90, v78, v78
	v_fmac_f32_e32 v91, v79, v79
	v_add_f32_e32 v88, v88, v89
	v_add_f32_e32 v90, v90, v91
	v_add_f32_e32 v84, v88, v90
	s_nop 1
	v_add_f32_dpp v84, v84, v84 quad_perm:[1,0,3,2] row_mask:0xf bank_mask:0xf bound_ctrl:1
	s_nop 1
	v_add_f32_dpp v84, v84, v84 quad_perm:[2,3,0,1] row_mask:0xf bank_mask:0xf bound_ctrl:1
	s_nop 1
	v_add_f32_dpp v84, v84, v84 row_half_mirror row_mask:0xf bank_mask:0xf bound_ctrl:1
	s_nop 1
	v_add_f32_dpp v84, v84, v84 row_mirror row_mask:0xf bank_mask:0xf bound_ctrl:1
	s_nop 0
	v_readlane_b32 s44, v84, 0
	v_readlane_b32 s46, v84, 16
	v_readlane_b32 s48, v84, 32
	v_readlane_b32 s50, v84, 48
	s_nop 0
	v_mov_b32_e32 v85, s44
	v_mov_b32_e32 v86, s48
	v_add_f32_e32 v85, s46, v85
	v_add_f32_e32 v86, s50, v86
	v_add_f32_e32 v84, v85, v86
	v_fmamk_f32 v84, v84, 0x3a800000, v130
	v_rsq_f32_e32 v84, v84
	s_nop 0
	v_mul_f32_e32 v92, v84, v64
	v_fmac_f32_e32 v48, v0, v92
	v_mul_f32_e32 v93, v84, v65
	v_fmac_f32_e32 v49, v1, v93
	v_mul_f32_e32 v94, v84, v66
	v_fmac_f32_e32 v50, v2, v94
	v_mul_f32_e32 v95, v84, v67
	v_fmac_f32_e32 v51, v3, v95
	v_mul_f32_e32 v92, v84, v68
	v_fmac_f32_e32 v52, v4, v92
	v_mul_f32_e32 v93, v84, v69
	v_fmac_f32_e32 v53, v5, v93
	v_mul_f32_e32 v94, v84, v70
	v_fmac_f32_e32 v54, v6, v94
	v_mul_f32_e32 v95, v84, v71
	v_fmac_f32_e32 v55, v7, v95
	v_mul_f32_e32 v92, v84, v72
	v_fmac_f32_e32 v56, v8, v92
	v_mul_f32_e32 v93, v84, v73
	v_fmac_f32_e32 v57, v9, v93
	v_mul_f32_e32 v94, v84, v74
	v_fmac_f32_e32 v58, v10, v94
	v_mul_f32_e32 v95, v84, v75
	v_fmac_f32_e32 v59, v11, v95
	v_mul_f32_e32 v92, v84, v76
	v_fmac_f32_e32 v60, v12, v92
	v_mul_f32_e32 v93, v84, v77
	v_fmac_f32_e32 v61, v13, v93
	v_mul_f32_e32 v94, v84, v78
	v_fmac_f32_e32 v62, v14, v94
	v_mul_f32_e32 v95, v84, v79
	v_fmac_f32_e32 v63, v15, v95
	s_lshl_b32 s21, s20, 11
	s_cmp_lg_u32 s34, 0
	s_cbranch_scc1 .Lgro11_r1_fin
	s_add_u32 s22, s86, s21
	s_addc_u32 s23, s87, 0
	v_cvt_pk_bf16_f32 v100, v48, v49
	v_cvt_pk_bf16_f32 v101, v50, v51
	v_cvt_pk_bf16_f32 v102, v52, v53
	v_cvt_pk_bf16_f32 v103, v54, v55
	v_cvt_pk_bf16_f32 v104, v56, v57
	v_cvt_pk_bf16_f32 v105, v58, v59
	v_cvt_pk_bf16_f32 v106, v60, v61
	v_cvt_pk_bf16_f32 v107, v62, v63
	global_store_dwordx4 v82, v[100:103], s[22:23]
	global_store_dwordx4 v82, v[104:107], s[22:23] offset:1024
	v_mul_f32_e32 v88, v48, v48
	v_mul_f32_e32 v89, v49, v49
	v_mul_f32_e32 v90, v50, v50
	v_mul_f32_e32 v91, v51, v51
	v_fmac_f32_e32 v88, v52, v52
	v_fmac_f32_e32 v89, v53, v53
	v_fmac_f32_e32 v90, v54, v54
	v_fmac_f32_e32 v91, v55, v55
	v_fmac_f32_e32 v88, v56, v56
	v_fmac_f32_e32 v89, v57, v57
	v_fmac_f32_e32 v90, v58, v58
	v_fmac_f32_e32 v91, v59, v59
	v_fmac_f32_e32 v88, v60, v60
	v_fmac_f32_e32 v89, v61, v61
	v_fmac_f32_e32 v90, v62, v62
	v_fmac_f32_e32 v91, v63, v63
	v_add_f32_e32 v88, v88, v89
	v_add_f32_e32 v90, v90, v91
	v_add_f32_e32 v84, v88, v90
	s_nop 1
	v_add_f32_dpp v84, v84, v84 quad_perm:[1,0,3,2] row_mask:0xf bank_mask:0xf bound_ctrl:1
	s_nop 1
	v_add_f32_dpp v84, v84, v84 quad_perm:[2,3,0,1] row_mask:0xf bank_mask:0xf bound_ctrl:1
	s_nop 1
	v_add_f32_dpp v84, v84, v84 row_half_mirror row_mask:0xf bank_mask:0xf bound_ctrl:1
	s_nop 1
	v_add_f32_dpp v84, v84, v84 row_mirror row_mask:0xf bank_mask:0xf bound_ctrl:1
	s_nop 0
	v_readlane_b32 s44, v84, 0
	v_readlane_b32 s46, v84, 16
	v_readlane_b32 s48, v84, 32
	v_readlane_b32 s50, v84, 48
	s_nop 0
	v_mov_b32_e32 v85, s44
	v_mov_b32_e32 v86, s48
	v_add_f32_e32 v85, s46, v85
	v_add_f32_e32 v86, s50, v86
	v_add_f32_e32 v84, v85, v86
	v_fmamk_f32 v84, v84, 0x3a800000, v130
	v_rsq_f32_e32 v84, v84
	s_nop 0
	v_mul_f32_e32 v92, v48, v84
	v_fma_f32 v64, v92, v32, v16
	v_mul_f32_e32 v93, v49, v84
	v_fma_f32 v65, v93, v33, v17
	v_mul_f32_e32 v94, v50, v84
	v_fma_f32 v66, v94, v34, v18
	v_mul_f32_e32 v95, v51, v84
	v_fma_f32 v67, v95, v35, v19
	v_mul_f32_e32 v92, v52, v84
	v_fma_f32 v68, v92, v36, v20
	v_mul_f32_e32 v93, v53, v84
	v_fma_f32 v69, v93, v37, v21
	v_mul_f32_e32 v94, v54, v84
	v_fma_f32 v70, v94, v38, v22
	v_mul_f32_e32 v95, v55, v84
	v_fma_f32 v71, v95, v39, v23
	v_mul_f32_e32 v92, v56, v84
	v_fma_f32 v72, v92, v40, v24
	v_mul_f32_e32 v93, v57, v84
	v_fma_f32 v73, v93, v41, v25
	v_mul_f32_e32 v94, v58, v84
	v_fma_f32 v74, v94, v42, v26
	v_mul_f32_e32 v95, v59, v84
	v_fma_f32 v75, v95, v43, v27
	v_mul_f32_e32 v92, v60, v84
	v_fma_f32 v76, v92, v44, v28
	v_mul_f32_e32 v93, v61, v84
	v_fma_f32 v77, v93, v45, v29
	v_mul_f32_e32 v94, v62, v84
	v_fma_f32 v78, v94, v46, v30
	v_mul_f32_e32 v95, v63, v84
	v_fma_f32 v79, v95, v47, v31
	s_add_u32 s22, s18, s21
	s_addc_u32 s23, s19, 0
	v_cvt_pk_bf16_f32 v108, v64, v65
	v_cvt_pk_bf16_f32 v109, v66, v67
	v_cvt_pk_bf16_f32 v110, v68, v69
	v_cvt_pk_bf16_f32 v111, v70, v71
	v_cvt_pk_bf16_f32 v112, v72, v73
	v_cvt_pk_bf16_f32 v113, v74, v75
	v_cvt_pk_bf16_f32 v114, v76, v77
	v_cvt_pk_bf16_f32 v115, v78, v79
	global_store_dwordx4 v82, v[108:111], s[22:23]
	global_store_dwordx4 v82, v[112:115], s[22:23] offset:1024
	s_branch .Lgro11_r1_done

.Lgro11_r2_same:
	s_waitcnt vmcnt(16)
.Lgro11_r2_go:
	v_lshlrev_b32_e32 v48, 16, v200
	v_and_b32_e32 v49, 0xffff0000, v200
	v_lshlrev_b32_e32 v50, 16, v201
	v_and_b32_e32 v51, 0xffff0000, v201
	v_lshlrev_b32_e32 v52, 16, v202
	v_and_b32_e32 v53, 0xffff0000, v202
	v_lshlrev_b32_e32 v54, 16, v203
	v_and_b32_e32 v55, 0xffff0000, v203
	v_lshlrev_b32_e32 v56, 16, v204
	v_and_b32_e32 v57, 0xffff0000, v204
	v_lshlrev_b32_e32 v58, 16, v205
	v_and_b32_e32 v59, 0xffff0000, v205
	v_lshlrev_b32_e32 v60, 16, v206
	v_and_b32_e32 v61, 0xffff0000, v206
	v_lshlrev_b32_e32 v62, 16, v207
	v_and_b32_e32 v63, 0xffff0000, v207
	v_lshlrev_b32_e32 v64, 16, v208
	v_and_b32_e32 v65, 0xffff0000, v208
	v_lshlrev_b32_e32 v66, 16, v209
	v_and_b32_e32 v67, 0xffff0000, v209
	v_lshlrev_b32_e32 v68, 16, v210
	v_and_b32_e32 v69, 0xffff0000, v210
	v_lshlrev_b32_e32 v70, 16, v211
	v_and_b32_e32 v71, 0xffff0000, v211
	v_lshlrev_b32_e32 v72, 16, v212
	v_and_b32_e32 v73, 0xffff0000, v212
	v_lshlrev_b32_e32 v74, 16, v213
	v_and_b32_e32 v75, 0xffff0000, v213
	v_lshlrev_b32_e32 v76, 16, v214
	v_and_b32_e32 v77, 0xffff0000, v214
	v_lshlrev_b32_e32 v78, 16, v215
	v_and_b32_e32 v79, 0xffff0000, v215
	v_mul_f32_e32 v88, v64, v64
	v_mul_f32_e32 v89, v65, v65
	v_mul_f32_e32 v90, v66, v66
	v_mul_f32_e32 v91, v67, v67
	v_fmac_f32_e32 v88, v68, v68
	v_fmac_f32_e32 v89, v69, v69
	v_fmac_f32_e32 v90, v70, v70
	v_fmac_f32_e32 v91, v71, v71
	v_fmac_f32_e32 v88, v72, v72
	v_fmac_f32_e32 v89, v73, v73
	v_fmac_f32_e32 v90, v74, v74
	v_fmac_f32_e32 v91, v75, v75
	v_fmac_f32_e32 v88, v76, v76
	v_fmac_f32_e32 v89, v77, v77
	v_fmac_f32_e32 v90, v78, v78
	v_fmac_f32_e32 v91, v79, v79
	v_add_f32_e32 v88, v88, v89
	v_add_f32_e32 v90, v90, v91
	v_add_f32_e32 v84, v88, v90
	s_nop 1
	v_add_f32_dpp v84, v84, v84 quad_perm:[1,0,3,2] row_mask:0xf bank_mask:0xf bound_ctrl:1
	s_nop 1
	v_add_f32_dpp v84, v84, v84 quad_perm:[2,3,0,1] row_mask:0xf bank_mask:0xf bound_ctrl:1
	s_nop 1
	v_add_f32_dpp v84, v84, v84 row_half_mirror row_mask:0xf bank_mask:0xf bound_ctrl:1
	s_nop 1
	v_add_f32_dpp v84, v84, v84 row_mirror row_mask:0xf bank_mask:0xf bound_ctrl:1
	s_nop 0
	v_readlane_b32 s44, v84, 0
	v_readlane_b32 s46, v84, 16
	v_readlane_b32 s48, v84, 32
	v_readlane_b32 s50, v84, 48
	s_nop 0
	v_mov_b32_e32 v85, s44
	v_mov_b32_e32 v86, s48
	v_add_f32_e32 v85, s46, v85
	v_add_f32_e32 v86, s50, v86
	v_add_f32_e32 v84, v85, v86
	v_fmamk_f32 v84, v84, 0x3a800000, v130
	v_rsq_f32_e32 v84, v84
	s_nop 0
	v_mul_f32_e32 v92, v84, v64
	v_fmac_f32_e32 v48, v0, v92
	v_mul_f32_e32 v93, v84, v65
	v_fmac_f32_e32 v49, v1, v93
	v_mul_f32_e32 v94, v84, v66
	v_fmac_f32_e32 v50, v2, v94
	v_mul_f32_e32 v95, v84, v67
	v_fmac_f32_e32 v51, v3, v95
	v_mul_f32_e32 v92, v84, v68
	v_fmac_f32_e32 v52, v4, v92
	v_mul_f32_e32 v93, v84, v69
	v_fmac_f32_e32 v53, v5, v93
	v_mul_f32_e32 v94, v84, v70
	v_fmac_f32_e32 v54, v6, v94
	v_mul_f32_e32 v95, v84, v71
	v_fmac_f32_e32 v55, v7, v95
	v_mul_f32_e32 v92, v84, v72
	v_fmac_f32_e32 v56, v8, v92
	v_mul_f32_e32 v93, v84, v73
	v_fmac_f32_e32 v57, v9, v93
	v_mul_f32_e32 v94, v84, v74
	v_fmac_f32_e32 v58, v10, v94
	v_mul_f32_e32 v95, v84, v75
	v_fmac_f32_e32 v59, v11, v95
	v_mul_f32_e32 v92, v84, v76
	v_fmac_f32_e32 v60, v12, v92
	v_mul_f32_e32 v93, v84, v77
	v_fmac_f32_e32 v61, v13, v93
	v_mul_f32_e32 v94, v84, v78
	v_fmac_f32_e32 v62, v14, v94
	v_mul_f32_e32 v95, v84, v79
	v_fmac_f32_e32 v63, v15, v95
	s_lshl_b32 s21, s20, 11
	s_cmp_lg_u32 s34, 0
	s_cbranch_scc1 .Lgro11_r2_fin
	s_add_u32 s22, s86, s21
	s_addc_u32 s23, s87, 0
	v_cvt_pk_bf16_f32 v100, v48, v49
	v_cvt_pk_bf16_f32 v101, v50, v51
	v_cvt_pk_bf16_f32 v102, v52, v53
	v_cvt_pk_bf16_f32 v103, v54, v55
	v_cvt_pk_bf16_f32 v104, v56, v57
	v_cvt_pk_bf16_f32 v105, v58, v59
	v_cvt_pk_bf16_f32 v106, v60, v61
	v_cvt_pk_bf16_f32 v107, v62, v63
	global_store_dwordx4 v82, v[100:103], s[22:23]
	global_store_dwordx4 v82, v[104:107], s[22:23] offset:1024
	v_mul_f32_e32 v88, v48, v48
	v_mul_f32_e32 v89, v49, v49
	v_mul_f32_e32 v90, v50, v50
	v_mul_f32_e32 v91, v51, v51
	v_fmac_f32_e32 v88, v52, v52
	v_fmac_f32_e32 v89, v53, v53
	v_fmac_f32_e32 v90, v54, v54
	v_fmac_f32_e32 v91, v55, v55
	v_fmac_f32_e32 v88, v56, v56
	v_fmac_f32_e32 v89, v57, v57
	v_fmac_f32_e32 v90, v58, v58
	v_fmac_f32_e32 v91, v59, v59
	v_fmac_f32_e32 v88, v60, v60
	v_fmac_f32_e32 v89, v61, v61
	v_fmac_f32_e32 v90, v62, v62
	v_fmac_f32_e32 v91, v63, v63
	v_add_f32_e32 v88, v88, v89
	v_add_f32_e32 v90, v90, v91
	v_add_f32_e32 v84, v88, v90
	s_nop 1
	v_add_f32_dpp v84, v84, v84 quad_perm:[1,0,3,2] row_mask:0xf bank_mask:0xf bound_ctrl:1
	s_nop 1
	v_add_f32_dpp v84, v84, v84 quad_perm:[2,3,0,1] row_mask:0xf bank_mask:0xf bound_ctrl:1
	s_nop 1
	v_add_f32_dpp v84, v84, v84 row_half_mirror row_mask:0xf bank_mask:0xf bound_ctrl:1
	s_nop 1
	v_add_f32_dpp v84, v84, v84 row_mirror row_mask:0xf bank_mask:0xf bound_ctrl:1
	s_nop 0
	v_readlane_b32 s44, v84, 0
	v_readlane_b32 s46, v84, 16
	v_readlane_b32 s48, v84, 32
	v_readlane_b32 s50, v84, 48
	s_nop 0
	v_mov_b32_e32 v85, s44
	v_mov_b32_e32 v86, s48
	v_add_f32_e32 v85, s46, v85
	v_add_f32_e32 v86, s50, v86
	v_add_f32_e32 v84, v85, v86
	v_fmamk_f32 v84, v84, 0x3a800000, v130
	v_rsq_f32_e32 v84, v84
	s_nop 0
	v_mul_f32_e32 v92, v48, v84
	v_fma_f32 v64, v92, v32, v16
	v_mul_f32_e32 v93, v49, v84
	v_fma_f32 v65, v93, v33, v17
	v_mul_f32_e32 v94, v50, v84
	v_fma_f32 v66, v94, v34, v18
	v_mul_f32_e32 v95, v51, v84
	v_fma_f32 v67, v95, v35, v19
	v_mul_f32_e32 v92, v52, v84
	v_fma_f32 v68, v92, v36, v20
	v_mul_f32_e32 v93, v53, v84
	v_fma_f32 v69, v93, v37, v21
	v_mul_f32_e32 v94, v54, v84
	v_fma_f32 v70, v94, v38, v22
	v_mul_f32_e32 v95, v55, v84
	v_fma_f32 v71, v95, v39, v23
	v_mul_f32_e32 v92, v56, v84
	v_fma_f32 v72, v92, v40, v24
	v_mul_f32_e32 v93, v57, v84
	v_fma_f32 v73, v93, v41, v25
	v_mul_f32_e32 v94, v58, v84
	v_fma_f32 v74, v94, v42, v26
	v_mul_f32_e32 v95, v59, v84
	v_fma_f32 v75, v95, v43, v27
	v_mul_f32_e32 v92, v60, v84
	v_fma_f32 v76, v92, v44, v28
	v_mul_f32_e32 v93, v61, v84
	v_fma_f32 v77, v93, v45, v29
	v_mul_f32_e32 v94, v62, v84
	v_fma_f32 v78, v94, v46, v30
	v_mul_f32_e32 v95, v63, v84
	v_fma_f32 v79, v95, v47, v31
	s_add_u32 s22, s18, s21
	s_addc_u32 s23, s19, 0
	v_cvt_pk_bf16_f32 v108, v64, v65
	v_cvt_pk_bf16_f32 v109, v66, v67
	v_cvt_pk_bf16_f32 v110, v68, v69
	v_cvt_pk_bf16_f32 v111, v70, v71
	v_cvt_pk_bf16_f32 v112, v72, v73
	v_cvt_pk_bf16_f32 v113, v74, v75
	v_cvt_pk_bf16_f32 v114, v76, v77
	v_cvt_pk_bf16_f32 v115, v78, v79
	global_store_dwordx4 v82, v[108:111], s[22:23]
	global_store_dwordx4 v82, v[112:115], s[22:23] offset:1024
	s_branch .Lgro11_r2_done

.Lgro11_r3_same:
	s_waitcnt vmcnt(16)
.Lgro11_r3_go:
	v_lshlrev_b32_e32 v48, 16, v216
	v_and_b32_e32 v49, 0xffff0000, v216
	v_lshlrev_b32_e32 v50, 16, v217
	v_and_b32_e32 v51, 0xffff0000, v217
	v_lshlrev_b32_e32 v52, 16, v218
	v_and_b32_e32 v53, 0xffff0000, v218
	v_lshlrev_b32_e32 v54, 16, v219
	v_and_b32_e32 v55, 0xffff0000, v219
	v_lshlrev_b32_e32 v56, 16, v220
	v_and_b32_e32 v57, 0xffff0000, v220
	v_lshlrev_b32_e32 v58, 16, v221
	v_and_b32_e32 v59, 0xffff0000, v221
	v_lshlrev_b32_e32 v60, 16, v222
	v_and_b32_e32 v61, 0xffff0000, v222
	v_lshlrev_b32_e32 v62, 16, v223
	v_and_b32_e32 v63, 0xffff0000, v223
	v_lshlrev_b32_e32 v64, 16, v224
	v_and_b32_e32 v65, 0xffff0000, v224
	v_lshlrev_b32_e32 v66, 16, v225
	v_and_b32_e32 v67, 0xffff0000, v225
	v_lshlrev_b32_e32 v68, 16, v226
	v_and_b32_e32 v69, 0xffff0000, v226
	v_lshlrev_b32_e32 v70, 16, v227
	v_and_b32_e32 v71, 0xffff0000, v227
	v_lshlrev_b32_e32 v72, 16, v228
	v_and_b32_e32 v73, 0xffff0000, v228
	v_lshlrev_b32_e32 v74, 16, v229
	v_and_b32_e32 v75, 0xffff0000, v229
	v_lshlrev_b32_e32 v76, 16, v230
	v_and_b32_e32 v77, 0xffff0000, v230
	v_lshlrev_b32_e32 v78, 16, v231
	v_and_b32_e32 v79, 0xffff0000, v231
	v_mul_f32_e32 v88, v64, v64
	v_mul_f32_e32 v89, v65, v65
	v_mul_f32_e32 v90, v66, v66
	v_mul_f32_e32 v91, v67, v67
	v_fmac_f32_e32 v88, v68, v68
	v_fmac_f32_e32 v89, v69, v69
	v_fmac_f32_e32 v90, v70, v70
	v_fmac_f32_e32 v91, v71, v71
	v_fmac_f32_e32 v88, v72, v72
	v_fmac_f32_e32 v89, v73, v73
	v_fmac_f32_e32 v90, v74, v74
	v_fmac_f32_e32 v91, v75, v75
	v_fmac_f32_e32 v88, v76, v76
	v_fmac_f32_e32 v89, v77, v77
	v_fmac_f32_e32 v90, v78, v78
	v_fmac_f32_e32 v91, v79, v79
	v_add_f32_e32 v88, v88, v89
	v_add_f32_e32 v90, v90, v91
	v_add_f32_e32 v84, v88, v90
	s_nop 1
	v_add_f32_dpp v84, v84, v84 quad_perm:[1,0,3,2] row_mask:0xf bank_mask:0xf bound_ctrl:1
	s_nop 1
	v_add_f32_dpp v84, v84, v84 quad_perm:[2,3,0,1] row_mask:0xf bank_mask:0xf bound_ctrl:1
	s_nop 1
	v_add_f32_dpp v84, v84, v84 row_half_mirror row_mask:0xf bank_mask:0xf bound_ctrl:1
	s_nop 1
	v_add_f32_dpp v84, v84, v84 row_mirror row_mask:0xf bank_mask:0xf bound_ctrl:1
	s_nop 0
	v_readlane_b32 s44, v84, 0
	v_readlane_b32 s46, v84, 16
	v_readlane_b32 s48, v84, 32
	v_readlane_b32 s50, v84, 48
	s_nop 0
	v_mov_b32_e32 v85, s44
	v_mov_b32_e32 v86, s48
	v_add_f32_e32 v85, s46, v85
	v_add_f32_e32 v86, s50, v86
	v_add_f32_e32 v84, v85, v86
	v_fmamk_f32 v84, v84, 0x3a800000, v130
	v_rsq_f32_e32 v84, v84
	s_nop 0
	v_mul_f32_e32 v92, v84, v64
	v_fmac_f32_e32 v48, v0, v92
	v_mul_f32_e32 v93, v84, v65
	v_fmac_f32_e32 v49, v1, v93
	v_mul_f32_e32 v94, v84, v66
	v_fmac_f32_e32 v50, v2, v94
	v_mul_f32_e32 v95, v84, v67
	v_fmac_f32_e32 v51, v3, v95
	v_mul_f32_e32 v92, v84, v68
	v_fmac_f32_e32 v52, v4, v92
	v_mul_f32_e32 v93, v84, v69
	v_fmac_f32_e32 v53, v5, v93
	v_mul_f32_e32 v94, v84, v70
	v_fmac_f32_e32 v54, v6, v94
	v_mul_f32_e32 v95, v84, v71
	v_fmac_f32_e32 v55, v7, v95
	v_mul_f32_e32 v92, v84, v72
	v_fmac_f32_e32 v56, v8, v92
	v_mul_f32_e32 v93, v84, v73
	v_fmac_f32_e32 v57, v9, v93
	v_mul_f32_e32 v94, v84, v74
	v_fmac_f32_e32 v58, v10, v94
	v_mul_f32_e32 v95, v84, v75
	v_fmac_f32_e32 v59, v11, v95
	v_mul_f32_e32 v92, v84, v76
	v_fmac_f32_e32 v60, v12, v92
	v_mul_f32_e32 v93, v84, v77
	v_fmac_f32_e32 v61, v13, v93
	v_mul_f32_e32 v94, v84, v78
	v_fmac_f32_e32 v62, v14, v94
	v_mul_f32_e32 v95, v84, v79
	v_fmac_f32_e32 v63, v15, v95
	s_lshl_b32 s21, s20, 11
	s_cmp_lg_u32 s34, 0
	s_cbranch_scc1 .Lgro11_r3_fin
	s_add_u32 s22, s86, s21
	s_addc_u32 s23, s87, 0
	v_cvt_pk_bf16_f32 v100, v48, v49
	v_cvt_pk_bf16_f32 v101, v50, v51
	v_cvt_pk_bf16_f32 v102, v52, v53
	v_cvt_pk_bf16_f32 v103, v54, v55
	v_cvt_pk_bf16_f32 v104, v56, v57
	v_cvt_pk_bf16_f32 v105, v58, v59
	v_cvt_pk_bf16_f32 v106, v60, v61
	v_cvt_pk_bf16_f32 v107, v62, v63
	global_store_dwordx4 v82, v[100:103], s[22:23]
	global_store_dwordx4 v82, v[104:107], s[22:23] offset:1024
	v_mul_f32_e32 v88, v48, v48
	v_mul_f32_e32 v89, v49, v49
	v_mul_f32_e32 v90, v50, v50
	v_mul_f32_e32 v91, v51, v51
	v_fmac_f32_e32 v88, v52, v52
	v_fmac_f32_e32 v89, v53, v53
	v_fmac_f32_e32 v90, v54, v54
	v_fmac_f32_e32 v91, v55, v55
	v_fmac_f32_e32 v88, v56, v56
	v_fmac_f32_e32 v89, v57, v57
	v_fmac_f32_e32 v90, v58, v58
	v_fmac_f32_e32 v91, v59, v59
	v_fmac_f32_e32 v88, v60, v60
	v_fmac_f32_e32 v89, v61, v61
	v_fmac_f32_e32 v90, v62, v62
	v_fmac_f32_e32 v91, v63, v63
	v_add_f32_e32 v88, v88, v89
	v_add_f32_e32 v90, v90, v91
	v_add_f32_e32 v84, v88, v90
	s_nop 1
	v_add_f32_dpp v84, v84, v84 quad_perm:[1,0,3,2] row_mask:0xf bank_mask:0xf bound_ctrl:1
	s_nop 1
	v_add_f32_dpp v84, v84, v84 quad_perm:[2,3,0,1] row_mask:0xf bank_mask:0xf bound_ctrl:1
	s_nop 1
	v_add_f32_dpp v84, v84, v84 row_half_mirror row_mask:0xf bank_mask:0xf bound_ctrl:1
	s_nop 1
	v_add_f32_dpp v84, v84, v84 row_mirror row_mask:0xf bank_mask:0xf bound_ctrl:1
	s_nop 0
	v_readlane_b32 s44, v84, 0
	v_readlane_b32 s46, v84, 16
	v_readlane_b32 s48, v84, 32
	v_readlane_b32 s50, v84, 48
	s_nop 0
	v_mov_b32_e32 v85, s44
	v_mov_b32_e32 v86, s48
	v_add_f32_e32 v85, s46, v85
	v_add_f32_e32 v86, s50, v86
	v_add_f32_e32 v84, v85, v86
	v_fmamk_f32 v84, v84, 0x3a800000, v130
	v_rsq_f32_e32 v84, v84
	s_nop 0
	v_mul_f32_e32 v92, v48, v84
	v_fma_f32 v64, v92, v32, v16
	v_mul_f32_e32 v93, v49, v84
	v_fma_f32 v65, v93, v33, v17
	v_mul_f32_e32 v94, v50, v84
	v_fma_f32 v66, v94, v34, v18
	v_mul_f32_e32 v95, v51, v84
	v_fma_f32 v67, v95, v35, v19
	v_mul_f32_e32 v92, v52, v84
	v_fma_f32 v68, v92, v36, v20
	v_mul_f32_e32 v93, v53, v84
	v_fma_f32 v69, v93, v37, v21
	v_mul_f32_e32 v94, v54, v84
	v_fma_f32 v70, v94, v38, v22
	v_mul_f32_e32 v95, v55, v84
	v_fma_f32 v71, v95, v39, v23
	v_mul_f32_e32 v92, v56, v84
	v_fma_f32 v72, v92, v40, v24
	v_mul_f32_e32 v93, v57, v84
	v_fma_f32 v73, v93, v41, v25
	v_mul_f32_e32 v94, v58, v84
	v_fma_f32 v74, v94, v42, v26
	v_mul_f32_e32 v95, v59, v84
	v_fma_f32 v75, v95, v43, v27
	v_mul_f32_e32 v92, v60, v84
	v_fma_f32 v76, v92, v44, v28
	v_mul_f32_e32 v93, v61, v84
	v_fma_f32 v77, v93, v45, v29
	v_mul_f32_e32 v94, v62, v84
	v_fma_f32 v78, v94, v46, v30
	v_mul_f32_e32 v95, v63, v84
	v_fma_f32 v79, v95, v47, v31
	s_add_u32 s22, s18, s21
	s_addc_u32 s23, s19, 0
	v_cvt_pk_bf16_f32 v108, v64, v65
	v_cvt_pk_bf16_f32 v109, v66, v67
	v_cvt_pk_bf16_f32 v110, v68, v69
	v_cvt_pk_bf16_f32 v111, v70, v71
	v_cvt_pk_bf16_f32 v112, v72, v73
	v_cvt_pk_bf16_f32 v113, v74, v75
	v_cvt_pk_bf16_f32 v114, v76, v77
	v_cvt_pk_bf16_f32 v115, v78, v79
	global_store_dwordx4 v82, v[108:111], s[22:23]
	global_store_dwordx4 v82, v[112:115], s[22:23] offset:1024
	s_branch .Lgro11_r3_done

.Lgro11_r4_same:
	s_waitcnt vmcnt(16)
.Lgro11_r4_go:
	v_lshlrev_b32_e32 v48, 16, v232
	v_and_b32_e32 v49, 0xffff0000, v232
	v_lshlrev_b32_e32 v50, 16, v233
	v_and_b32_e32 v51, 0xffff0000, v233
	v_lshlrev_b32_e32 v52, 16, v234
	v_and_b32_e32 v53, 0xffff0000, v234
	v_lshlrev_b32_e32 v54, 16, v235
	v_and_b32_e32 v55, 0xffff0000, v235
	v_lshlrev_b32_e32 v56, 16, v236
	v_and_b32_e32 v57, 0xffff0000, v236
	v_lshlrev_b32_e32 v58, 16, v237
	v_and_b32_e32 v59, 0xffff0000, v237
	v_lshlrev_b32_e32 v60, 16, v238
	v_and_b32_e32 v61, 0xffff0000, v238
	v_lshlrev_b32_e32 v62, 16, v239
	v_and_b32_e32 v63, 0xffff0000, v239
	v_lshlrev_b32_e32 v64, 16, v240
	v_and_b32_e32 v65, 0xffff0000, v240
	v_lshlrev_b32_e32 v66, 16, v241
	v_and_b32_e32 v67, 0xffff0000, v241
	v_lshlrev_b32_e32 v68, 16, v242
	v_and_b32_e32 v69, 0xffff0000, v242
	v_lshlrev_b32_e32 v70, 16, v243
	v_and_b32_e32 v71, 0xffff0000, v243
	v_lshlrev_b32_e32 v72, 16, v244
	v_and_b32_e32 v73, 0xffff0000, v244
	v_lshlrev_b32_e32 v74, 16, v245
	v_and_b32_e32 v75, 0xffff0000, v245
	v_lshlrev_b32_e32 v76, 16, v246
	v_and_b32_e32 v77, 0xffff0000, v246
	v_lshlrev_b32_e32 v78, 16, v247
	v_and_b32_e32 v79, 0xffff0000, v247
	v_mul_f32_e32 v88, v64, v64
	v_mul_f32_e32 v89, v65, v65
	v_mul_f32_e32 v90, v66, v66
	v_mul_f32_e32 v91, v67, v67
	v_fmac_f32_e32 v88, v68, v68
	v_fmac_f32_e32 v89, v69, v69
	v_fmac_f32_e32 v90, v70, v70
	v_fmac_f32_e32 v91, v71, v71
	v_fmac_f32_e32 v88, v72, v72
	v_fmac_f32_e32 v89, v73, v73
	v_fmac_f32_e32 v90, v74, v74
	v_fmac_f32_e32 v91, v75, v75
	v_fmac_f32_e32 v88, v76, v76
	v_fmac_f32_e32 v89, v77, v77
	v_fmac_f32_e32 v90, v78, v78
	v_fmac_f32_e32 v91, v79, v79
	v_add_f32_e32 v88, v88, v89
	v_add_f32_e32 v90, v90, v91
	v_add_f32_e32 v84, v88, v90
	s_nop 1
	v_add_f32_dpp v84, v84, v84 quad_perm:[1,0,3,2] row_mask:0xf bank_mask:0xf bound_ctrl:1
	s_nop 1
	v_add_f32_dpp v84, v84, v84 quad_perm:[2,3,0,1] row_mask:0xf bank_mask:0xf bound_ctrl:1
	s_nop 1
	v_add_f32_dpp v84, v84, v84 row_half_mirror row_mask:0xf bank_mask:0xf bound_ctrl:1
	s_nop 1
	v_add_f32_dpp v84, v84, v84 row_mirror row_mask:0xf bank_mask:0xf bound_ctrl:1
	s_nop 0
	v_readlane_b32 s44, v84, 0
	v_readlane_b32 s46, v84, 16
	v_readlane_b32 s48, v84, 32
	v_readlane_b32 s50, v84, 48
	s_nop 0
	v_mov_b32_e32 v85, s44
	v_mov_b32_e32 v86, s48
	v_add_f32_e32 v85, s46, v85
	v_add_f32_e32 v86, s50, v86
	v_add_f32_e32 v84, v85, v86
	v_fmamk_f32 v84, v84, 0x3a800000, v130
	v_rsq_f32_e32 v84, v84
	s_nop 0
	v_mul_f32_e32 v92, v84, v64
	v_fmac_f32_e32 v48, v0, v92
	v_mul_f32_e32 v93, v84, v65
	v_fmac_f32_e32 v49, v1, v93
	v_mul_f32_e32 v94, v84, v66
	v_fmac_f32_e32 v50, v2, v94
	v_mul_f32_e32 v95, v84, v67
	v_fmac_f32_e32 v51, v3, v95
	v_mul_f32_e32 v92, v84, v68
	v_fmac_f32_e32 v52, v4, v92
	v_mul_f32_e32 v93, v84, v69
	v_fmac_f32_e32 v53, v5, v93
	v_mul_f32_e32 v94, v84, v70
	v_fmac_f32_e32 v54, v6, v94
	v_mul_f32_e32 v95, v84, v71
	v_fmac_f32_e32 v55, v7, v95
	v_mul_f32_e32 v92, v84, v72
	v_fmac_f32_e32 v56, v8, v92
	v_mul_f32_e32 v93, v84, v73
	v_fmac_f32_e32 v57, v9, v93
	v_mul_f32_e32 v94, v84, v74
	v_fmac_f32_e32 v58, v10, v94
	v_mul_f32_e32 v95, v84, v75
	v_fmac_f32_e32 v59, v11, v95
	v_mul_f32_e32 v92, v84, v76
	v_fmac_f32_e32 v60, v12, v92
	v_mul_f32_e32 v93, v84, v77
	v_fmac_f32_e32 v61, v13, v93
	v_mul_f32_e32 v94, v84, v78
	v_fmac_f32_e32 v62, v14, v94
	v_mul_f32_e32 v95, v84, v79
	v_fmac_f32_e32 v63, v15, v95
	s_lshl_b32 s21, s20, 11
	s_cmp_lg_u32 s34, 0
	s_cbranch_scc1 .Lgro11_r4_fin
	s_add_u32 s22, s86, s21
	s_addc_u32 s23, s87, 0
	v_cvt_pk_bf16_f32 v100, v48, v49
	v_cvt_pk_bf16_f32 v101, v50, v51
	v_cvt_pk_bf16_f32 v102, v52, v53
	v_cvt_pk_bf16_f32 v103, v54, v55
	v_cvt_pk_bf16_f32 v104, v56, v57
	v_cvt_pk_bf16_f32 v105, v58, v59
	v_cvt_pk_bf16_f32 v106, v60, v61
	v_cvt_pk_bf16_f32 v107, v62, v63
	global_store_dwordx4 v82, v[100:103], s[22:23]
	global_store_dwordx4 v82, v[104:107], s[22:23] offset:1024
	v_mul_f32_e32 v88, v48, v48
	v_mul_f32_e32 v89, v49, v49
	v_mul_f32_e32 v90, v50, v50
	v_mul_f32_e32 v91, v51, v51
	v_fmac_f32_e32 v88, v52, v52
	v_fmac_f32_e32 v89, v53, v53
	v_fmac_f32_e32 v90, v54, v54
	v_fmac_f32_e32 v91, v55, v55
	v_fmac_f32_e32 v88, v56, v56
	v_fmac_f32_e32 v89, v57, v57
	v_fmac_f32_e32 v90, v58, v58
	v_fmac_f32_e32 v91, v59, v59
	v_fmac_f32_e32 v88, v60, v60
	v_fmac_f32_e32 v89, v61, v61
	v_fmac_f32_e32 v90, v62, v62
	v_fmac_f32_e32 v91, v63, v63
	v_add_f32_e32 v88, v88, v89
	v_add_f32_e32 v90, v90, v91
	v_add_f32_e32 v84, v88, v90
	s_nop 1
	v_add_f32_dpp v84, v84, v84 quad_perm:[1,0,3,2] row_mask:0xf bank_mask:0xf bound_ctrl:1
	s_nop 1
	v_add_f32_dpp v84, v84, v84 quad_perm:[2,3,0,1] row_mask:0xf bank_mask:0xf bound_ctrl:1
	s_nop 1
	v_add_f32_dpp v84, v84, v84 row_half_mirror row_mask:0xf bank_mask:0xf bound_ctrl:1
	s_nop 1
	v_add_f32_dpp v84, v84, v84 row_mirror row_mask:0xf bank_mask:0xf bound_ctrl:1
	s_nop 0
	v_readlane_b32 s44, v84, 0
	v_readlane_b32 s46, v84, 16
	v_readlane_b32 s48, v84, 32
	v_readlane_b32 s50, v84, 48
	s_nop 0
	v_mov_b32_e32 v85, s44
	v_mov_b32_e32 v86, s48
	v_add_f32_e32 v85, s46, v85
	v_add_f32_e32 v86, s50, v86
	v_add_f32_e32 v84, v85, v86
	v_fmamk_f32 v84, v84, 0x3a800000, v130
	v_rsq_f32_e32 v84, v84
	s_nop 0
	v_mul_f32_e32 v92, v48, v84
	v_fma_f32 v64, v92, v32, v16
	v_mul_f32_e32 v93, v49, v84
	v_fma_f32 v65, v93, v33, v17
	v_mul_f32_e32 v94, v50, v84
	v_fma_f32 v66, v94, v34, v18
	v_mul_f32_e32 v95, v51, v84
	v_fma_f32 v67, v95, v35, v19
	v_mul_f32_e32 v92, v52, v84
	v_fma_f32 v68, v92, v36, v20
	v_mul_f32_e32 v93, v53, v84
	v_fma_f32 v69, v93, v37, v21
	v_mul_f32_e32 v94, v54, v84
	v_fma_f32 v70, v94, v38, v22
	v_mul_f32_e32 v95, v55, v84
	v_fma_f32 v71, v95, v39, v23
	v_mul_f32_e32 v92, v56, v84
	v_fma_f32 v72, v92, v40, v24
	v_mul_f32_e32 v93, v57, v84
	v_fma_f32 v73, v93, v41, v25
	v_mul_f32_e32 v94, v58, v84
	v_fma_f32 v74, v94, v42, v26
	v_mul_f32_e32 v95, v59, v84
	v_fma_f32 v75, v95, v43, v27
	v_mul_f32_e32 v92, v60, v84
	v_fma_f32 v76, v92, v44, v28
	v_mul_f32_e32 v93, v61, v84
	v_fma_f32 v77, v93, v45, v29
	v_mul_f32_e32 v94, v62, v84
	v_fma_f32 v78, v94, v46, v30
	v_mul_f32_e32 v95, v63, v84
	v_fma_f32 v79, v95, v47, v31
	s_add_u32 s22, s18, s21
	s_addc_u32 s23, s19, 0
	v_cvt_pk_bf16_f32 v108, v64, v65
	v_cvt_pk_bf16_f32 v109, v66, v67
	v_cvt_pk_bf16_f32 v110, v68, v69
	v_cvt_pk_bf16_f32 v111, v70, v71
	v_cvt_pk_bf16_f32 v112, v72, v73
	v_cvt_pk_bf16_f32 v113, v74, v75
	v_cvt_pk_bf16_f32 v114, v76, v77
	v_cvt_pk_bf16_f32 v115, v78, v79
	global_store_dwordx4 v82, v[108:111], s[22:23]
	global_store_dwordx4 v82, v[112:115], s[22:23] offset:1024
	s_branch .Lgro11_r4_done
